# GEMM K-loops: equal-priority window after every 8 MFMAs (was one per 32-MFMA block) so the loading partner wave can issue
# speedup vs baseline: 1.0045x; 1.0045x over previous
; #define PG8_STAGE(bufoff, gbase, voff) do { _Pragma("unroll") for (int _i = 0; _i < 2; ++_i) \
;         __builtin_amdgcn_global_load_lds((const unsigned*)((const char*)(gbase) + (voff)[_i]), (PG8_LAS unsigned*)(lds + (bufoff) + ldsw + _i * 8192), 16, 0, 0); } while (0)
; #define PG8_LDA(dst, b, h) do { _Pragma("unroll") for (int m = 0; m < 4; ++m) _Pragma("unroll") for (int k = 0; k < 2; ++k) dst[m][k] = *(const PG8_LAS bf16x8*)(lds + PG8_SA(b, h) + aoff + m * 2048 + k * 1024); } while (0)
; #define PG8_LDB(dst, b, h) do { _Pragma("unroll") for (int n = 0; n < 2; ++n) _Pragma("unroll") for (int k = 0; k < 2; ++k) dst[n][k] = *(const PG8_LAS bf16x8*)(lds + PG8_SB(b, h) + boff + n * 2048 + k * 1024); } while (0)
; #define PG8_MMA(ai, bj, At, Bt) do { __builtin_amdgcn_s_setprio(1); _Pragma("unroll") for (int m = 0; m < 4; ++m) _Pragma("unroll") for (int n = 0; n < 2; ++n) _Pragma("unroll") for (int k = 0; k < 2; ++k) \
;         acc[ai][bj][m][n] = __builtin_amdgcn_mfma_f32_16x16x32_bf16(Bt[n][k], At[m][k], acc[ai][bj][m][n], 0, 0, 0); __builtin_amdgcn_s_setprio(0); } while (0)
; #define PG8_WAIT_V(n) asm volatile("s_waitcnt vmcnt(" #n ")" ::: "memory")
; #define PG8_WAIT_L(n) asm volatile("s_waitcnt lgkmcnt(" #n ")" ::: "memory")
; #define PG8_BAR __builtin_amdgcn_s_barrier()
; #define PG8_SCHED __builtin_amdgcn_sched_barrier(0)
; template <class Epi, class Sched, bool ALIGN_EPI = false, bool SP2 = false>
; __device__ __forceinline__ void gemm_phase(PG8_LAS unsigned char* lds, const Gemm g, const Sched& S, const Epi& E) {
;     ...
;             if constexpr (SP2) {
;             PG8_LDB(B0, 0, 0); PG8_LDB(B1, 0, 1); PG8_SCHED; PG8_LDA(At, 0, 0); PG8_STAGE(PG8_SA(1, 1), a1 + hstep, voffA);
;             PG8_WAIT_V(8); PG8_WAIT_L(0); PG8_BAR; PG8_MMA(0, 0, At, B0); PG8_MMA(0, 1, At, B1); PG8_BAR; PG8_SCHED;
;             PG8_LDA(At, 0, 1); PG8_STAGE(PG8_SB(0, 0), b2, voffB); PG8_STAGE(PG8_SB(0, 1), b2 + hstepB, voffB); PG8_STAGE(PG8_SA(0, 0), a2, voffA);
.LBB0_33:
	s_add_u32 s18, s16, 0x100
	s_addc_u32 s19, s17, 0
	s_add_i32 s56, 0, 0x10000
	s_cmp_eq_u32 s55, 40
	s_cselect_b32 s23, s13, s19
	s_cselect_b32 s22, s12, s18
	s_cselect_b32 s21, s15, s43
	s_cselect_b32 s20, s14, s42
	s_add_i32 s57, 0, 0x14000
	v_add_u32_e32 v140, s56, v169
	v_add_u32_e32 v166, s57, v169
	ds_read_b128 v[112:115], v140
	ds_read_b128 v[124:127], v140 offset:1024
	ds_read_b128 v[128:131], v140 offset:2048
	ds_read_b128 v[140:143], v140 offset:3072
	ds_read_b128 v[154:157], v166
	ds_read_b128 v[158:161], v166 offset:1024
	ds_read_b128 v[162:165], v166 offset:2048
	ds_read_b128 v[172:175], v166 offset:3072
	v_lshl_add_u64 v[166:167], s[16:17], 0, v[152:153]
	s_add_i32 m0, s33, 0xc000
	ds_read_b128 v[176:179], v171
	ds_read_b128 v[180:183], v171 offset:1024
	ds_read_b128 v[184:187], v171 offset:2048
	ds_read_b128 v[188:191], v171 offset:3072
	ds_read_b128 v[206:209], v171 offset:4096
	ds_read_b128 v[210:213], v171 offset:5120
	ds_read_b128 v[214:217], v171 offset:6144
	ds_read_b128 v[224:227], v171 offset:7168
	global_load_lds_dwordx4 v[166:167], off
	v_lshl_add_u64 v[166:167], s[16:17], 0, v[150:151]
	s_add_i32 m0, s33, 0xe000
	s_nop 0
	global_load_lds_dwordx4 v[166:167], off
	s_waitcnt vmcnt(8)
	s_waitcnt lgkmcnt(0)
	s_barrier
	s_setprio 1
	s_waitcnt lgkmcnt(0)
	v_mfma_f32_16x16x32_bf16 v[136:139], v[112:115], v[176:179], v[136:139]
	v_mfma_f32_16x16x32_bf16 v[132:135], v[128:131], v[176:179], v[132:135]
	v_mfma_f32_16x16x32_bf16 v[108:111], v[112:115], v[184:187], v[108:111]
	v_mfma_f32_16x16x32_bf16 v[104:107], v[128:131], v[184:187], v[104:107]
	v_mfma_f32_16x16x32_bf16 v[92:95], v[112:115], v[206:209], v[92:95]
	v_mfma_f32_16x16x32_bf16 v[88:91], v[128:131], v[206:209], v[88:91]
	v_mfma_f32_16x16x32_bf16 v[76:79], v[112:115], v[214:217], v[76:79]
	v_mfma_f32_16x16x32_bf16 v[72:75], v[128:131], v[214:217], v[72:75]
	s_setprio 0
	s_setprio 1
	v_mfma_f32_16x16x32_bf16 v[136:139], v[124:127], v[180:183], v[136:139]
	v_mfma_f32_16x16x32_bf16 v[132:135], v[140:143], v[180:183], v[132:135]
	v_mfma_f32_16x16x32_bf16 v[108:111], v[124:127], v[188:191], v[108:111]
	v_mfma_f32_16x16x32_bf16 v[104:107], v[140:143], v[188:191], v[104:107]
	v_mfma_f32_16x16x32_bf16 v[92:95], v[124:127], v[210:213], v[92:95]
	v_mfma_f32_16x16x32_bf16 v[88:91], v[140:143], v[210:213], v[88:91]
	v_mfma_f32_16x16x32_bf16 v[76:79], v[124:127], v[224:227], v[76:79]
	v_mfma_f32_16x16x32_bf16 v[72:75], v[140:143], v[224:227], v[72:75]
	s_setprio 0
	s_setprio 1
	v_mfma_f32_16x16x32_bf16 v[120:123], v[154:157], v[176:179], v[120:123]
	v_mfma_f32_16x16x32_bf16 v[116:119], v[162:165], v[176:179], v[116:119]
	v_mfma_f32_16x16x32_bf16 v[100:103], v[154:157], v[184:187], v[100:103]
	v_mfma_f32_16x16x32_bf16 v[96:99], v[162:165], v[184:187], v[96:99]
	v_mfma_f32_16x16x32_bf16 v[84:87], v[154:157], v[206:209], v[84:87]
	v_mfma_f32_16x16x32_bf16 v[80:83], v[162:165], v[206:209], v[80:83]
	v_mfma_f32_16x16x32_bf16 v[68:71], v[154:157], v[214:217], v[68:71]
	v_mfma_f32_16x16x32_bf16 v[64:67], v[162:165], v[214:217], v[64:67]
	s_setprio 0
	s_setprio 1
	v_mfma_f32_16x16x32_bf16 v[120:123], v[158:161], v[180:183], v[120:123]
	v_mfma_f32_16x16x32_bf16 v[116:119], v[172:175], v[180:183], v[116:119]
	v_mfma_f32_16x16x32_bf16 v[100:103], v[158:161], v[188:191], v[100:103]
	v_mfma_f32_16x16x32_bf16 v[96:99], v[172:175], v[188:191], v[96:99]
	v_mfma_f32_16x16x32_bf16 v[84:87], v[158:161], v[210:213], v[84:87]
	v_mfma_f32_16x16x32_bf16 v[80:83], v[172:175], v[210:213], v[80:83]
	v_mfma_f32_16x16x32_bf16 v[68:71], v[158:161], v[224:227], v[68:71]
	v_mfma_f32_16x16x32_bf16 v[64:67], v[172:175], v[224:227], v[64:67]
	s_setprio 0
	s_barrier
	s_add_i32 s16, s56, s29
	v_lshl_add_u64 v[166:167], s[20:21], 0, v[192:193]
	s_mov_b32 m0, s16
	ds_read_b128 v[176:179], v171 offset:16384
	ds_read_b128 v[180:183], v171 offset:17408
	ds_read_b128 v[184:187], v171 offset:18432
	ds_read_b128 v[188:191], v171 offset:19456
	ds_read_b128 v[206:209], v171 offset:20480
	ds_read_b128 v[210:213], v171 offset:21504
	ds_read_b128 v[214:217], v171 offset:22528
	ds_read_b128 v[224:227], v171 offset:23552
	global_load_lds_dwordx4 v[166:167], off
	s_add_i32 m0, s16, 0x2000
	s_add_u32 s16, s20, 0x2c000
	v_lshl_add_u64 v[228:229], s[20:21], 0, v[144:145]
	s_addc_u32 s17, s21, 0
	s_add_i32 s56, s57, s29
	global_load_lds_dwordx4 v[228:229], off
	v_lshl_add_u64 v[230:231], s[16:17], 0, v[192:193]
	s_mov_b32 m0, s56
	v_lshl_add_u64 v[232:233], s[22:23], 0, v[146:147]
	global_load_lds_dwordx4 v[230:231], off
	v_lshl_add_u64 v[230:231], s[16:17], 0, v[144:145]
	s_add_i32 m0, s56, 0x2000
	s_nop 0
	global_load_lds_dwordx4 v[230:231], off
	v_lshl_add_u64 v[230:231], s[22:23], 0, v[148:149]
	s_mov_b32 m0, s33
	s_nop 0
	global_load_lds_dwordx4 v[230:231], off
	s_mov_b32 m0, s44
	s_nop 0
	global_load_lds_dwordx4 v[232:233], off
	s_waitcnt vmcnt(8)
	s_waitcnt lgkmcnt(0)
	s_barrier
; #define PG8_STAGE(bufoff, gbase, voff) do { _Pragma("unroll") for (int _i = 0; _i < 2; ++_i) \
;         __builtin_amdgcn_global_load_lds((const unsigned*)((const char*)(gbase) + (voff)[_i]), (PG8_LAS unsigned*)(lds + (bufoff) + ldsw + _i * 8192), 16, 0, 0); } while (0)
; #define PG8_LDA(dst, b, h) do { _Pragma("unroll") for (int m = 0; m < 4; ++m) _Pragma("unroll") for (int k = 0; k < 2; ++k) dst[m][k] = *(const PG8_LAS bf16x8*)(lds + PG8_SA(b, h) + aoff + m * 2048 + k * 1024); } while (0)
; #define PG8_LDB(dst, b, h) do { _Pragma("unroll") for (int n = 0; n < 2; ++n) _Pragma("unroll") for (int k = 0; k < 2; ++k) dst[n][k] = *(const PG8_LAS bf16x8*)(lds + PG8_SB(b, h) + boff + n * 2048 + k * 1024); } while (0)
; #define PG8_MMA(ai, bj, At, Bt) do { __builtin_amdgcn_s_setprio(1); _Pragma("unroll") for (int m = 0; m < 4; ++m) _Pragma("unroll") for (int n = 0; n < 2; ++n) _Pragma("unroll") for (int k = 0; k < 2; ++k) \
;         acc[ai][bj][m][n] = __builtin_amdgcn_mfma_f32_16x16x32_bf16(Bt[n][k], At[m][k], acc[ai][bj][m][n], 0, 0, 0); __builtin_amdgcn_s_setprio(0); } while (0)
; #define PG8_WAIT_V(n) asm volatile("s_waitcnt vmcnt(" #n ")" ::: "memory")
; #define PG8_WAIT_L(n) asm volatile("s_waitcnt lgkmcnt(" #n ")" ::: "memory")
; #define PG8_BAR __builtin_amdgcn_s_barrier()
; #define PG8_SCHED __builtin_amdgcn_sched_barrier(0)
; template <class Epi, class Sched, bool ALIGN_EPI = false, bool SP2 = false>
; __device__ __forceinline__ void gemm_phase(PG8_LAS unsigned char* lds, const Gemm g, const Sched& S, const Epi& E) {
;     ...
;             PG8_WAIT_V(8); PG8_WAIT_L(0); PG8_BAR; PG8_MMA(1, 0, At, B0); PG8_MMA(1, 1, At, B1); PG8_BAR; PG8_SCHED;
;             PG8_LDB(B0, 1, 0); PG8_LDB(B1, 1, 1); PG8_SCHED; PG8_LDA(At, 1, 0); PG8_STAGE(PG8_SA(0, 1), a2 + hstep, voffA);
;             PG8_WAIT_V(8); PG8_WAIT_L(0); PG8_BAR; PG8_MMA(0, 0, At, B0); PG8_MMA(0, 1, At, B1); PG8_BAR; PG8_SCHED;
	s_setprio 1
	s_waitcnt lgkmcnt(0)
	v_mfma_f32_16x16x32_bf16 v[60:63], v[112:115], v[176:179], v[60:63]
	v_mfma_f32_16x16x32_bf16 v[56:59], v[128:131], v[176:179], v[56:59]
	v_mfma_f32_16x16x32_bf16 v[44:47], v[112:115], v[184:187], v[44:47]
	v_mfma_f32_16x16x32_bf16 v[40:43], v[128:131], v[184:187], v[40:43]
	v_mfma_f32_16x16x32_bf16 v[28:31], v[112:115], v[206:209], v[28:31]
	v_mfma_f32_16x16x32_bf16 v[24:27], v[128:131], v[206:209], v[24:27]
	v_mfma_f32_16x16x32_bf16 v[12:15], v[112:115], v[214:217], v[12:15]
	v_mfma_f32_16x16x32_bf16 v[8:11], v[128:131], v[214:217], v[8:11]
	s_setprio 0
	s_setprio 1
	v_mfma_f32_16x16x32_bf16 v[60:63], v[124:127], v[180:183], v[60:63]
	v_mfma_f32_16x16x32_bf16 v[56:59], v[140:143], v[180:183], v[56:59]
	v_mfma_f32_16x16x32_bf16 v[44:47], v[124:127], v[188:191], v[44:47]
	v_mfma_f32_16x16x32_bf16 v[40:43], v[140:143], v[188:191], v[40:43]
	v_mfma_f32_16x16x32_bf16 v[28:31], v[124:127], v[210:213], v[28:31]
	v_mfma_f32_16x16x32_bf16 v[24:27], v[140:143], v[210:213], v[24:27]
	v_mfma_f32_16x16x32_bf16 v[12:15], v[124:127], v[224:227], v[12:15]
	v_mfma_f32_16x16x32_bf16 v[8:11], v[140:143], v[224:227], v[8:11]
	s_setprio 0
	s_setprio 1
	v_mfma_f32_16x16x32_bf16 v[52:55], v[154:157], v[176:179], v[52:55]
	v_mfma_f32_16x16x32_bf16 v[48:51], v[162:165], v[176:179], v[48:51]
	v_mfma_f32_16x16x32_bf16 v[36:39], v[154:157], v[184:187], v[36:39]
	v_mfma_f32_16x16x32_bf16 v[32:35], v[162:165], v[184:187], v[32:35]
	v_mfma_f32_16x16x32_bf16 v[20:23], v[154:157], v[206:209], v[20:23]
	v_mfma_f32_16x16x32_bf16 v[16:19], v[162:165], v[206:209], v[16:19]
	v_mfma_f32_16x16x32_bf16 v[4:7], v[154:157], v[214:217], v[4:7]
	v_mfma_f32_16x16x32_bf16 v[0:3], v[162:165], v[214:217], v[0:3]
	s_setprio 0
	s_setprio 1
	v_mfma_f32_16x16x32_bf16 v[52:55], v[158:161], v[180:183], v[52:55]
	v_mfma_f32_16x16x32_bf16 v[48:51], v[172:175], v[180:183], v[48:51]
	v_mfma_f32_16x16x32_bf16 v[36:39], v[158:161], v[188:191], v[36:39]
	v_mfma_f32_16x16x32_bf16 v[32:35], v[172:175], v[188:191], v[32:35]
	v_mfma_f32_16x16x32_bf16 v[20:23], v[158:161], v[210:213], v[20:23]
	v_mfma_f32_16x16x32_bf16 v[16:19], v[172:175], v[210:213], v[16:19]
	v_mfma_f32_16x16x32_bf16 v[4:7], v[158:161], v[224:227], v[4:7]
	v_mfma_f32_16x16x32_bf16 v[0:3], v[172:175], v[224:227], v[0:3]
	s_setprio 0
	s_barrier
	s_add_i32 s56, 0, 0x18000
	s_add_i32 s57, 0, 0x1c000
	v_add_u32_e32 v140, s56, v169
	v_add_u32_e32 v172, s57, v169
	ds_read_b128 v[112:115], v140
	ds_read_b128 v[124:127], v140 offset:1024
	ds_read_b128 v[128:131], v140 offset:2048
	ds_read_b128 v[140:143], v140 offset:3072
	ds_read_b128 v[154:157], v172
	ds_read_b128 v[158:161], v172 offset:1024
	ds_read_b128 v[162:165], v172 offset:2048
	ds_read_b128 v[172:175], v172 offset:3072
	s_add_u32 s16, s22, 0xb0000
	s_addc_u32 s17, s23, 0
	s_mov_b32 m0, s45
	v_lshl_add_u64 v[234:235], s[16:17], 0, v[148:149]
	ds_read_b128 v[176:179], v171 offset:32768
	ds_read_b128 v[180:183], v171 offset:33792
	ds_read_b128 v[184:187], v171 offset:34816
	ds_read_b128 v[188:191], v171 offset:35840
	ds_read_b128 v[206:209], v171 offset:36864
	ds_read_b128 v[210:213], v171 offset:37888
	ds_read_b128 v[214:217], v171 offset:38912
	ds_read_b128 v[224:227], v171 offset:39936
	global_load_lds_dwordx4 v[234:235], off
	v_lshl_add_u64 v[234:235], s[16:17], 0, v[146:147]
	s_mov_b32 m0, s46
	s_nop 0
	global_load_lds_dwordx4 v[234:235], off
	s_waitcnt vmcnt(8)
	s_waitcnt lgkmcnt(0)
	s_barrier
	s_setprio 1
	s_waitcnt lgkmcnt(0)
	v_mfma_f32_16x16x32_bf16 v[136:139], v[112:115], v[176:179], v[136:139]
	v_mfma_f32_16x16x32_bf16 v[132:135], v[128:131], v[176:179], v[132:135]
	v_mfma_f32_16x16x32_bf16 v[108:111], v[112:115], v[184:187], v[108:111]
	v_mfma_f32_16x16x32_bf16 v[104:107], v[128:131], v[184:187], v[104:107]
	v_mfma_f32_16x16x32_bf16 v[92:95], v[112:115], v[206:209], v[92:95]
	v_mfma_f32_16x16x32_bf16 v[88:91], v[128:131], v[206:209], v[88:91]
	v_mfma_f32_16x16x32_bf16 v[76:79], v[112:115], v[214:217], v[76:79]
	v_mfma_f32_16x16x32_bf16 v[72:75], v[128:131], v[214:217], v[72:75]
	s_setprio 0
	s_setprio 1
	v_mfma_f32_16x16x32_bf16 v[136:139], v[124:127], v[180:183], v[136:139]
	v_mfma_f32_16x16x32_bf16 v[132:135], v[140:143], v[180:183], v[132:135]
	v_mfma_f32_16x16x32_bf16 v[108:111], v[124:127], v[188:191], v[108:111]
	v_mfma_f32_16x16x32_bf16 v[104:107], v[140:143], v[188:191], v[104:107]
	v_mfma_f32_16x16x32_bf16 v[92:95], v[124:127], v[210:213], v[92:95]
	v_mfma_f32_16x16x32_bf16 v[88:91], v[140:143], v[210:213], v[88:91]
	v_mfma_f32_16x16x32_bf16 v[76:79], v[124:127], v[224:227], v[76:79]
	v_mfma_f32_16x16x32_bf16 v[72:75], v[140:143], v[224:227], v[72:75]
	s_setprio 0
	s_setprio 1
	v_mfma_f32_16x16x32_bf16 v[120:123], v[154:157], v[176:179], v[120:123]
	v_mfma_f32_16x16x32_bf16 v[116:119], v[162:165], v[176:179], v[116:119]
	v_mfma_f32_16x16x32_bf16 v[100:103], v[154:157], v[184:187], v[100:103]
	v_mfma_f32_16x16x32_bf16 v[96:99], v[162:165], v[184:187], v[96:99]
	v_mfma_f32_16x16x32_bf16 v[84:87], v[154:157], v[206:209], v[84:87]
	v_mfma_f32_16x16x32_bf16 v[80:83], v[162:165], v[206:209], v[80:83]
	v_mfma_f32_16x16x32_bf16 v[68:71], v[154:157], v[214:217], v[68:71]
	v_mfma_f32_16x16x32_bf16 v[64:67], v[162:165], v[214:217], v[64:67]
	s_setprio 0
	s_setprio 1
	v_mfma_f32_16x16x32_bf16 v[120:123], v[158:161], v[180:183], v[120:123]
	v_mfma_f32_16x16x32_bf16 v[116:119], v[172:175], v[180:183], v[116:119]
	v_mfma_f32_16x16x32_bf16 v[100:103], v[158:161], v[188:191], v[100:103]
	v_mfma_f32_16x16x32_bf16 v[96:99], v[172:175], v[188:191], v[96:99]
	v_mfma_f32_16x16x32_bf16 v[84:87], v[158:161], v[210:213], v[84:87]
	v_mfma_f32_16x16x32_bf16 v[80:83], v[172:175], v[210:213], v[80:83]
	v_mfma_f32_16x16x32_bf16 v[68:71], v[158:161], v[224:227], v[68:71]
	v_mfma_f32_16x16x32_bf16 v[64:67], v[172:175], v[224:227], v[64:67]
	s_setprio 0
	s_barrier
; #define PG8_STAGE(bufoff, gbase, voff) do { _Pragma("unroll") for (int _i = 0; _i < 2; ++_i) \
;         __builtin_amdgcn_global_load_lds((const unsigned*)((const char*)(gbase) + (voff)[_i]), (PG8_LAS unsigned*)(lds + (bufoff) + ldsw + _i * 8192), 16, 0, 0); } while (0)
; #define PG8_LDA(dst, b, h) do { _Pragma("unroll") for (int m = 0; m < 4; ++m) _Pragma("unroll") for (int k = 0; k < 2; ++k) dst[m][k] = *(const PG8_LAS bf16x8*)(lds + PG8_SA(b, h) + aoff + m * 2048 + k * 1024); } while (0)
; #define PG8_MMA(ai, bj, At, Bt) do { __builtin_amdgcn_s_setprio(1); _Pragma("unroll") for (int m = 0; m < 4; ++m) _Pragma("unroll") for (int n = 0; n < 2; ++n) _Pragma("unroll") for (int k = 0; k < 2; ++k) \
;         acc[ai][bj][m][n] = __builtin_amdgcn_mfma_f32_16x16x32_bf16(Bt[n][k], At[m][k], acc[ai][bj][m][n], 0, 0, 0); __builtin_amdgcn_s_setprio(0); } while (0)
; #define PG8_WAIT_V(n) asm volatile("s_waitcnt vmcnt(" #n ")" ::: "memory")
; #define PG8_WAIT_L(n) asm volatile("s_waitcnt lgkmcnt(" #n ")" ::: "memory")
; #define PG8_BAR __builtin_amdgcn_s_barrier()
; #define PG8_SCHED __builtin_amdgcn_sched_barrier(0)
; template <class Epi, class Sched, bool ALIGN_EPI = false, bool SP2 = false>
; __device__ __forceinline__ void gemm_phase(PG8_LAS unsigned char* lds, const Gemm g, const Sched& S, const Epi& E) {
;     ...
;             PG8_LDA(At, 1, 1); PG8_STAGE(PG8_SB(1, 0), b3, voffB); PG8_STAGE(PG8_SB(1, 1), b3 + hstepB, voffB); PG8_STAGE(PG8_SA(1, 0), a3, voffA);
;             PG8_WAIT_V(8); PG8_WAIT_L(0); PG8_BAR; PG8_MMA(1, 0, At, B0); PG8_MMA(1, 1, At, B1); PG8_BAR; PG8_SCHED;
;     ...
;         if constexpr (ALIGN_EPI) { if (wr == 0) PG8_BAR; }
	s_add_i32 s16, s56, s29
	v_lshl_add_u64 v[166:167], v[166:167], 0, s[36:37]
	s_mov_b32 m0, s16
	ds_read_b128 v[176:179], v171 offset:49152
	ds_read_b128 v[180:183], v171 offset:50176
	ds_read_b128 v[184:187], v171 offset:51200
	ds_read_b128 v[188:191], v171 offset:52224
	ds_read_b128 v[206:209], v171 offset:53248
	ds_read_b128 v[210:213], v171 offset:54272
	ds_read_b128 v[214:217], v171 offset:55296
	ds_read_b128 v[224:227], v171 offset:56320
	global_load_lds_dwordx4 v[166:167], off
	s_add_i32 m0, s16, 0x2000
	s_add_u32 s16, s20, 0x2c080
	v_lshl_add_u64 v[166:167], v[228:229], 0, s[36:37]
	s_addc_u32 s17, s21, 0
	s_add_i32 s20, s57, s29
	global_load_lds_dwordx4 v[166:167], off
	v_lshl_add_u64 v[166:167], s[16:17], 0, v[192:193]
	s_mov_b32 m0, s20
	s_nop 0
	global_load_lds_dwordx4 v[166:167], off
	v_lshl_add_u64 v[166:167], s[16:17], 0, v[144:145]
	s_add_i32 m0, s20, 0x2000
	s_nop 0
	global_load_lds_dwordx4 v[166:167], off
	v_lshl_add_u64 v[166:167], v[230:231], 0, s[36:37]
	s_mov_b32 m0, s48
	s_nop 0
	global_load_lds_dwordx4 v[166:167], off
	v_lshl_add_u64 v[166:167], v[232:233], 0, s[36:37]
	s_mov_b32 m0, s49
	s_nop 0
	global_load_lds_dwordx4 v[166:167], off
	s_waitcnt vmcnt(8)
	s_waitcnt lgkmcnt(0)
	s_barrier
	s_setprio 1
	s_waitcnt lgkmcnt(0)
	v_mfma_f32_16x16x32_bf16 v[60:63], v[112:115], v[176:179], v[60:63]
	v_mfma_f32_16x16x32_bf16 v[56:59], v[128:131], v[176:179], v[56:59]
	v_mfma_f32_16x16x32_bf16 v[44:47], v[112:115], v[184:187], v[44:47]
	v_mfma_f32_16x16x32_bf16 v[40:43], v[128:131], v[184:187], v[40:43]
	v_mfma_f32_16x16x32_bf16 v[28:31], v[112:115], v[206:209], v[28:31]
	v_mfma_f32_16x16x32_bf16 v[24:27], v[128:131], v[206:209], v[24:27]
	v_mfma_f32_16x16x32_bf16 v[12:15], v[112:115], v[214:217], v[12:15]
	v_mfma_f32_16x16x32_bf16 v[8:11], v[128:131], v[214:217], v[8:11]
	s_setprio 0
	s_setprio 1
	v_mfma_f32_16x16x32_bf16 v[60:63], v[124:127], v[180:183], v[60:63]
	v_mfma_f32_16x16x32_bf16 v[56:59], v[140:143], v[180:183], v[56:59]
	v_mfma_f32_16x16x32_bf16 v[44:47], v[124:127], v[188:191], v[44:47]
	v_mfma_f32_16x16x32_bf16 v[40:43], v[140:143], v[188:191], v[40:43]
	v_mfma_f32_16x16x32_bf16 v[28:31], v[124:127], v[210:213], v[28:31]
	v_mfma_f32_16x16x32_bf16 v[24:27], v[140:143], v[210:213], v[24:27]
	v_mfma_f32_16x16x32_bf16 v[12:15], v[124:127], v[224:227], v[12:15]
	v_mfma_f32_16x16x32_bf16 v[8:11], v[140:143], v[224:227], v[8:11]
	s_setprio 0
	s_setprio 1
	v_mfma_f32_16x16x32_bf16 v[52:55], v[154:157], v[176:179], v[52:55]
	v_mfma_f32_16x16x32_bf16 v[48:51], v[162:165], v[176:179], v[48:51]
	v_mfma_f32_16x16x32_bf16 v[36:39], v[154:157], v[184:187], v[36:39]
	v_mfma_f32_16x16x32_bf16 v[32:35], v[162:165], v[184:187], v[32:35]
	v_mfma_f32_16x16x32_bf16 v[20:23], v[154:157], v[206:209], v[20:23]
	v_mfma_f32_16x16x32_bf16 v[16:19], v[162:165], v[206:209], v[16:19]
	v_mfma_f32_16x16x32_bf16 v[4:7], v[154:157], v[214:217], v[4:7]
	v_mfma_f32_16x16x32_bf16 v[0:3], v[162:165], v[214:217], v[0:3]
	s_setprio 0
	s_setprio 1
	v_mfma_f32_16x16x32_bf16 v[52:55], v[158:161], v[180:183], v[52:55]
	v_mfma_f32_16x16x32_bf16 v[48:51], v[172:175], v[180:183], v[48:51]
	v_mfma_f32_16x16x32_bf16 v[36:39], v[158:161], v[188:191], v[36:39]
	v_mfma_f32_16x16x32_bf16 v[32:35], v[172:175], v[188:191], v[32:35]
	v_mfma_f32_16x16x32_bf16 v[20:23], v[158:161], v[210:213], v[20:23]
	v_mfma_f32_16x16x32_bf16 v[16:19], v[172:175], v[210:213], v[16:19]
	v_mfma_f32_16x16x32_bf16 v[4:7], v[158:161], v[224:227], v[4:7]
	v_mfma_f32_16x16x32_bf16 v[0:3], v[172:175], v[224:227], v[0:3]
	s_setprio 0
	s_barrier
	s_add_i32 s55, s55, 2
	s_add_u32 s42, s42, 0x100
	s_addc_u32 s43, s43, 0
	s_cmp_gt_u32 s55, 41
	s_mov_b64 s[16:17], s[18:19]
	s_cbranch_scc0 .LBB0_33
	s_and_b64 vcc, exec, s[10:11]
	s_cbranch_vccz .LBB0_36
	s_barrier

; #define PG8_STAGE(bufoff, gbase, voff) do { _Pragma("unroll") for (int _i = 0; _i < 2; ++_i) \
;         __builtin_amdgcn_global_load_lds((const unsigned*)((const char*)(gbase) + (voff)[_i]), (PG8_LAS unsigned*)(lds + (bufoff) + ldsw + _i * 8192), 16, 0, 0); } while (0)
; #define PG8_LDA(dst, b, h) do { _Pragma("unroll") for (int m = 0; m < 4; ++m) _Pragma("unroll") for (int k = 0; k < 2; ++k) dst[m][k] = *(const PG8_LAS bf16x8*)(lds + PG8_SA(b, h) + aoff + m * 2048 + k * 1024); } while (0)
; #define PG8_LDB(dst, b, h) do { _Pragma("unroll") for (int n = 0; n < 2; ++n) _Pragma("unroll") for (int k = 0; k < 2; ++k) dst[n][k] = *(const PG8_LAS bf16x8*)(lds + PG8_SB(b, h) + boff + n * 2048 + k * 1024); } while (0)
; #define PG8_MMA(ai, bj, At, Bt) do { __builtin_amdgcn_s_setprio(1); _Pragma("unroll") for (int m = 0; m < 4; ++m) _Pragma("unroll") for (int n = 0; n < 2; ++n) _Pragma("unroll") for (int k = 0; k < 2; ++k) \
;         acc[ai][bj][m][n] = __builtin_amdgcn_mfma_f32_16x16x32_bf16(Bt[n][k], At[m][k], acc[ai][bj][m][n], 0, 0, 0); __builtin_amdgcn_s_setprio(0); } while (0)
; #define PG8_WAIT_V(n) asm volatile("s_waitcnt vmcnt(" #n ")" ::: "memory")
; #define PG8_WAIT_L(n) asm volatile("s_waitcnt lgkmcnt(" #n ")" ::: "memory")
; #define PG8_BAR __builtin_amdgcn_s_barrier()
; #define PG8_SCHED __builtin_amdgcn_sched_barrier(0)
; template <class Epi, class Sched, bool ALIGN_EPI = false, bool SP2 = false>
; __device__ __forceinline__ void gemm_phase(PG8_LAS unsigned char* lds, const Gemm g, const Sched& S, const Epi& E) {
;     ...
;             if constexpr (SP2) {
;             PG8_LDB(B0, 0, 0); PG8_LDB(B1, 0, 1); PG8_SCHED; PG8_LDA(At, 0, 0); PG8_STAGE(PG8_SA(1, 1), a1 + hstep, voffA);
;             PG8_WAIT_V(8); PG8_WAIT_L(0); PG8_BAR; PG8_MMA(0, 0, At, B0); PG8_MMA(0, 1, At, B1); PG8_BAR; PG8_SCHED;
;             PG8_LDA(At, 0, 1); PG8_STAGE(PG8_SB(0, 0), b2, voffB); PG8_STAGE(PG8_SB(0, 1), b2 + hstepB, voffB); PG8_STAGE(PG8_SA(0, 0), a2, voffA);
.LBB0_77:
	s_add_u32 s56, s60, 0x100
	s_addc_u32 s57, s61, 0
	s_add_i32 s81, 0, 0x10000
	s_cmp_eq_u32 s80, 12
	s_cselect_b32 s65, s23, s57
	s_cselect_b32 s64, s22, s56
	s_cselect_b32 s63, s21, s79
	s_cselect_b32 s62, s77, s78
	s_add_i32 s82, 0, 0x14000
	v_add_u32_e32 v140, s81, v190
	v_add_u32_e32 v156, s82, v190
	ds_read_b128 v[116:119], v140
	ds_read_b128 v[132:135], v140 offset:1024
	ds_read_b128 v[136:139], v140 offset:2048
	ds_read_b128 v[140:143], v140 offset:3072
	ds_read_b128 v[144:147], v156
	ds_read_b128 v[148:151], v156 offset:1024
	ds_read_b128 v[152:155], v156 offset:2048
	ds_read_b128 v[156:159], v156 offset:3072
	v_lshl_add_u64 v[242:243], s[60:61], 0, v[184:185]
	s_add_i32 m0, s59, 0xc000
	ds_read_b128 v[160:163], v228
	ds_read_b128 v[164:167], v228 offset:1024
	ds_read_b128 v[168:171], v228 offset:2048
	ds_read_b128 v[172:175], v228 offset:3072
	ds_read_b128 v[186:189], v228 offset:4096
	ds_read_b128 v[230:233], v228 offset:5120
	ds_read_b128 v[234:237], v228 offset:6144
	ds_read_b128 v[238:241], v228 offset:7168
	global_load_lds_dwordx4 v[242:243], off
	v_lshl_add_u64 v[242:243], s[60:61], 0, v[182:183]
	s_add_i32 m0, s59, 0xe000
	s_nop 0
	global_load_lds_dwordx4 v[242:243], off
	s_waitcnt vmcnt(8)
	s_waitcnt lgkmcnt(0)
	s_barrier
	s_setprio 1
	s_waitcnt lgkmcnt(0)
	v_mfma_f32_16x16x32_bf16 v[112:115], v[116:119], v[160:163], v[112:115]
	v_mfma_f32_16x16x32_bf16 v[80:83], v[136:139], v[160:163], v[80:83]
	v_mfma_f32_16x16x32_bf16 v[108:111], v[116:119], v[168:171], v[108:111]
	v_mfma_f32_16x16x32_bf16 v[56:59], v[136:139], v[168:171], v[56:59]
	v_mfma_f32_16x16x32_bf16 v[128:131], v[116:119], v[186:189], v[128:131]
	v_mfma_f32_16x16x32_bf16 v[92:95], v[136:139], v[186:189], v[92:95]
	v_mfma_f32_16x16x32_bf16 v[124:127], v[116:119], v[234:237], v[124:127]
	v_mfma_f32_16x16x32_bf16 v[120:123], v[136:139], v[234:237], v[120:123]
	s_setprio 0
	s_setprio 1
	v_mfma_f32_16x16x32_bf16 v[112:115], v[132:135], v[164:167], v[112:115]
	v_mfma_f32_16x16x32_bf16 v[80:83], v[140:143], v[164:167], v[80:83]
	v_mfma_f32_16x16x32_bf16 v[108:111], v[132:135], v[172:175], v[108:111]
	v_mfma_f32_16x16x32_bf16 v[56:59], v[140:143], v[172:175], v[56:59]
	v_mfma_f32_16x16x32_bf16 v[128:131], v[132:135], v[230:233], v[128:131]
	v_mfma_f32_16x16x32_bf16 v[92:95], v[140:143], v[230:233], v[92:95]
	v_mfma_f32_16x16x32_bf16 v[124:127], v[132:135], v[238:241], v[124:127]
	v_mfma_f32_16x16x32_bf16 v[120:123], v[140:143], v[238:241], v[120:123]
	s_setprio 0
	s_setprio 1
	v_mfma_f32_16x16x32_bf16 v[104:107], v[144:147], v[160:163], v[104:107]
	v_mfma_f32_16x16x32_bf16 v[68:71], v[152:155], v[160:163], v[68:71]
	v_mfma_f32_16x16x32_bf16 v[100:103], v[144:147], v[168:171], v[100:103]
	v_mfma_f32_16x16x32_bf16 v[52:55], v[152:155], v[168:171], v[52:55]
	v_mfma_f32_16x16x32_bf16 v[96:99], v[144:147], v[186:189], v[96:99]
	v_mfma_f32_16x16x32_bf16 v[84:87], v[152:155], v[186:189], v[84:87]
	v_mfma_f32_16x16x32_bf16 v[88:91], v[144:147], v[234:237], v[88:91]
	v_mfma_f32_16x16x32_bf16 v[48:51], v[152:155], v[234:237], v[48:51]
	s_setprio 0
	s_setprio 1
	v_mfma_f32_16x16x32_bf16 v[104:107], v[148:151], v[164:167], v[104:107]
	v_mfma_f32_16x16x32_bf16 v[68:71], v[156:159], v[164:167], v[68:71]
	v_mfma_f32_16x16x32_bf16 v[100:103], v[148:151], v[172:175], v[100:103]
	v_mfma_f32_16x16x32_bf16 v[52:55], v[156:159], v[172:175], v[52:55]
	v_mfma_f32_16x16x32_bf16 v[96:99], v[148:151], v[230:233], v[96:99]
	v_mfma_f32_16x16x32_bf16 v[84:87], v[156:159], v[230:233], v[84:87]
	v_mfma_f32_16x16x32_bf16 v[88:91], v[148:151], v[238:241], v[88:91]
	v_mfma_f32_16x16x32_bf16 v[48:51], v[156:159], v[238:241], v[48:51]
	s_setprio 0
	s_barrier
	s_add_i32 s60, s81, s66
	v_lshl_add_u64 v[242:243], s[62:63], 0, v[192:193]
	s_mov_b32 m0, s60
	ds_read_b128 v[160:163], v228 offset:16384
	ds_read_b128 v[164:167], v228 offset:17408
	ds_read_b128 v[168:171], v228 offset:18432
	ds_read_b128 v[172:175], v228 offset:19456
	ds_read_b128 v[186:189], v228 offset:20480
	ds_read_b128 v[230:233], v228 offset:21504
	ds_read_b128 v[234:237], v228 offset:22528
	ds_read_b128 v[238:241], v228 offset:23552
	global_load_lds_dwordx4 v[242:243], off
	s_add_i32 m0, s60, 0x2000
	s_add_u32 s60, s62, 0x40000
	v_lshl_add_u64 v[244:245], s[62:63], 0, v[180:181]
	s_addc_u32 s61, s63, 0
	s_add_i32 s81, s82, s66
	global_load_lds_dwordx4 v[244:245], off
	v_lshl_add_u64 v[246:247], s[60:61], 0, v[192:193]
	s_mov_b32 m0, s81
	v_lshl_add_u64 v[248:249], s[64:65], 0, v[178:179]
	global_load_lds_dwordx4 v[246:247], off
	v_lshl_add_u64 v[246:247], s[60:61], 0, v[180:181]
	s_add_i32 m0, s81, 0x2000
	s_nop 0
	global_load_lds_dwordx4 v[246:247], off
	v_lshl_add_u64 v[246:247], s[64:65], 0, v[176:177]
	s_mov_b32 m0, s59
	s_nop 0
	global_load_lds_dwordx4 v[246:247], off
	s_mov_b32 m0, s67
	s_nop 0
	global_load_lds_dwordx4 v[248:249], off
	s_waitcnt vmcnt(8)
	s_waitcnt lgkmcnt(0)
	s_barrier
; #define PG8_STAGE(bufoff, gbase, voff) do { _Pragma("unroll") for (int _i = 0; _i < 2; ++_i) \
;         __builtin_amdgcn_global_load_lds((const unsigned*)((const char*)(gbase) + (voff)[_i]), (PG8_LAS unsigned*)(lds + (bufoff) + ldsw + _i * 8192), 16, 0, 0); } while (0)
; #define PG8_LDA(dst, b, h) do { _Pragma("unroll") for (int m = 0; m < 4; ++m) _Pragma("unroll") for (int k = 0; k < 2; ++k) dst[m][k] = *(const PG8_LAS bf16x8*)(lds + PG8_SA(b, h) + aoff + m * 2048 + k * 1024); } while (0)
; #define PG8_LDB(dst, b, h) do { _Pragma("unroll") for (int n = 0; n < 2; ++n) _Pragma("unroll") for (int k = 0; k < 2; ++k) dst[n][k] = *(const PG8_LAS bf16x8*)(lds + PG8_SB(b, h) + boff + n * 2048 + k * 1024); } while (0)
; #define PG8_MMA(ai, bj, At, Bt) do { __builtin_amdgcn_s_setprio(1); _Pragma("unroll") for (int m = 0; m < 4; ++m) _Pragma("unroll") for (int n = 0; n < 2; ++n) _Pragma("unroll") for (int k = 0; k < 2; ++k) \
;         acc[ai][bj][m][n] = __builtin_amdgcn_mfma_f32_16x16x32_bf16(Bt[n][k], At[m][k], acc[ai][bj][m][n], 0, 0, 0); __builtin_amdgcn_s_setprio(0); } while (0)
; #define PG8_WAIT_V(n) asm volatile("s_waitcnt vmcnt(" #n ")" ::: "memory")
; #define PG8_WAIT_L(n) asm volatile("s_waitcnt lgkmcnt(" #n ")" ::: "memory")
; #define PG8_BAR __builtin_amdgcn_s_barrier()
; #define PG8_SCHED __builtin_amdgcn_sched_barrier(0)
; template <class Epi, class Sched, bool ALIGN_EPI = false, bool SP2 = false>
; __device__ __forceinline__ void gemm_phase(PG8_LAS unsigned char* lds, const Gemm g, const Sched& S, const Epi& E) {
;     ...
;             PG8_WAIT_V(8); PG8_WAIT_L(0); PG8_BAR; PG8_MMA(1, 0, At, B0); PG8_MMA(1, 1, At, B1); PG8_BAR; PG8_SCHED;
;             PG8_LDB(B0, 1, 0); PG8_LDB(B1, 1, 1); PG8_SCHED; PG8_LDA(At, 1, 0); PG8_STAGE(PG8_SA(0, 1), a2 + hstep, voffA);
;             PG8_WAIT_V(8); PG8_WAIT_L(0); PG8_BAR; PG8_MMA(0, 0, At, B0); PG8_MMA(0, 1, At, B1); PG8_BAR; PG8_SCHED;
	s_setprio 1
	s_waitcnt lgkmcnt(0)
	v_mfma_f32_16x16x32_bf16 v[36:39], v[116:119], v[160:163], v[36:39]
	v_mfma_f32_16x16x32_bf16 v[12:15], v[136:139], v[160:163], v[12:15]
	v_mfma_f32_16x16x32_bf16 v[24:27], v[116:119], v[168:171], v[24:27]
	v_mfma_f32_16x16x32_bf16 v[4:7], v[136:139], v[168:171], v[4:7]
	v_mfma_f32_16x16x32_bf16 v[64:67], v[116:119], v[186:189], v[64:67]
	v_mfma_f32_16x16x32_bf16 v[32:35], v[136:139], v[186:189], v[32:35]
	v_mfma_f32_16x16x32_bf16 v[76:79], v[116:119], v[234:237], v[76:79]
	v_mfma_f32_16x16x32_bf16 v[40:43], v[136:139], v[234:237], v[40:43]
	s_setprio 0
	s_setprio 1
	v_mfma_f32_16x16x32_bf16 v[36:39], v[132:135], v[164:167], v[36:39]
	v_mfma_f32_16x16x32_bf16 v[12:15], v[140:143], v[164:167], v[12:15]
	v_mfma_f32_16x16x32_bf16 v[24:27], v[132:135], v[172:175], v[24:27]
	v_mfma_f32_16x16x32_bf16 v[4:7], v[140:143], v[172:175], v[4:7]
	v_mfma_f32_16x16x32_bf16 v[64:67], v[132:135], v[230:233], v[64:67]
	v_mfma_f32_16x16x32_bf16 v[32:35], v[140:143], v[230:233], v[32:35]
	v_mfma_f32_16x16x32_bf16 v[76:79], v[132:135], v[238:241], v[76:79]
	v_mfma_f32_16x16x32_bf16 v[40:43], v[140:143], v[238:241], v[40:43]
	s_setprio 0
	s_setprio 1
	v_mfma_f32_16x16x32_bf16 v[20:23], v[144:147], v[160:163], v[20:23]
	v_mfma_f32_16x16x32_bf16 v[8:11], v[152:155], v[160:163], v[8:11]
	v_mfma_f32_16x16x32_bf16 v[16:19], v[144:147], v[168:171], v[16:19]
	v_mfma_f32_16x16x32_bf16 v[0:3], v[152:155], v[168:171], v[0:3]
	v_mfma_f32_16x16x32_bf16 v[60:63], v[144:147], v[186:189], v[60:63]
	v_mfma_f32_16x16x32_bf16 v[28:31], v[152:155], v[186:189], v[28:31]
	v_mfma_f32_16x16x32_bf16 v[72:75], v[144:147], v[234:237], v[72:75]
	v_mfma_f32_16x16x32_bf16 v[44:47], v[152:155], v[234:237], v[44:47]
	s_setprio 0
	s_setprio 1
	v_mfma_f32_16x16x32_bf16 v[20:23], v[148:151], v[164:167], v[20:23]
	v_mfma_f32_16x16x32_bf16 v[8:11], v[156:159], v[164:167], v[8:11]
	v_mfma_f32_16x16x32_bf16 v[16:19], v[148:151], v[172:175], v[16:19]
	v_mfma_f32_16x16x32_bf16 v[0:3], v[156:159], v[172:175], v[0:3]
	v_mfma_f32_16x16x32_bf16 v[60:63], v[148:151], v[230:233], v[60:63]
	v_mfma_f32_16x16x32_bf16 v[28:31], v[156:159], v[230:233], v[28:31]
	v_mfma_f32_16x16x32_bf16 v[72:75], v[148:151], v[238:241], v[72:75]
	v_mfma_f32_16x16x32_bf16 v[44:47], v[156:159], v[238:241], v[44:47]
	s_setprio 0
	s_barrier
	s_add_i32 s81, 0, 0x18000
	s_add_i32 s82, 0, 0x1c000
	v_add_u32_e32 v140, s81, v190
	v_add_u32_e32 v156, s82, v190
	ds_read_b128 v[116:119], v140
	ds_read_b128 v[132:135], v140 offset:1024
	ds_read_b128 v[136:139], v140 offset:2048
	ds_read_b128 v[140:143], v140 offset:3072
	ds_read_b128 v[144:147], v156
	ds_read_b128 v[148:151], v156 offset:1024
	ds_read_b128 v[152:155], v156 offset:2048
	ds_read_b128 v[156:159], v156 offset:3072
	s_add_u32 s60, s64, 0x40000
	s_addc_u32 s61, s65, 0
	s_mov_b32 m0, s68
	v_lshl_add_u64 v[250:251], s[60:61], 0, v[176:177]
	ds_read_b128 v[160:163], v228 offset:32768
	ds_read_b128 v[164:167], v228 offset:33792
	ds_read_b128 v[168:171], v228 offset:34816
	ds_read_b128 v[172:175], v228 offset:35840
	ds_read_b128 v[186:189], v228 offset:36864
	ds_read_b128 v[230:233], v228 offset:37888
	ds_read_b128 v[234:237], v228 offset:38912
	ds_read_b128 v[238:241], v228 offset:39936
	global_load_lds_dwordx4 v[250:251], off
	v_lshl_add_u64 v[250:251], s[60:61], 0, v[178:179]
	s_mov_b32 m0, s69
	s_nop 0
	global_load_lds_dwordx4 v[250:251], off
	s_waitcnt vmcnt(8)
	s_waitcnt lgkmcnt(0)
	s_barrier
	s_setprio 1
	s_waitcnt lgkmcnt(0)
	v_mfma_f32_16x16x32_bf16 v[112:115], v[116:119], v[160:163], v[112:115]
	v_mfma_f32_16x16x32_bf16 v[80:83], v[136:139], v[160:163], v[80:83]
	v_mfma_f32_16x16x32_bf16 v[108:111], v[116:119], v[168:171], v[108:111]
	v_mfma_f32_16x16x32_bf16 v[56:59], v[136:139], v[168:171], v[56:59]
	v_mfma_f32_16x16x32_bf16 v[128:131], v[116:119], v[186:189], v[128:131]
	v_mfma_f32_16x16x32_bf16 v[92:95], v[136:139], v[186:189], v[92:95]
	v_mfma_f32_16x16x32_bf16 v[124:127], v[116:119], v[234:237], v[124:127]
	v_mfma_f32_16x16x32_bf16 v[120:123], v[136:139], v[234:237], v[120:123]
	s_setprio 0
	s_setprio 1
	v_mfma_f32_16x16x32_bf16 v[112:115], v[132:135], v[164:167], v[112:115]
	v_mfma_f32_16x16x32_bf16 v[80:83], v[140:143], v[164:167], v[80:83]
	v_mfma_f32_16x16x32_bf16 v[108:111], v[132:135], v[172:175], v[108:111]
	v_mfma_f32_16x16x32_bf16 v[56:59], v[140:143], v[172:175], v[56:59]
	v_mfma_f32_16x16x32_bf16 v[128:131], v[132:135], v[230:233], v[128:131]
	v_mfma_f32_16x16x32_bf16 v[92:95], v[140:143], v[230:233], v[92:95]
	v_mfma_f32_16x16x32_bf16 v[124:127], v[132:135], v[238:241], v[124:127]
	v_mfma_f32_16x16x32_bf16 v[120:123], v[140:143], v[238:241], v[120:123]
	s_setprio 0
	s_setprio 1
	v_mfma_f32_16x16x32_bf16 v[104:107], v[144:147], v[160:163], v[104:107]
	v_mfma_f32_16x16x32_bf16 v[68:71], v[152:155], v[160:163], v[68:71]
	v_mfma_f32_16x16x32_bf16 v[100:103], v[144:147], v[168:171], v[100:103]
	v_mfma_f32_16x16x32_bf16 v[52:55], v[152:155], v[168:171], v[52:55]
	v_mfma_f32_16x16x32_bf16 v[96:99], v[144:147], v[186:189], v[96:99]
	v_mfma_f32_16x16x32_bf16 v[84:87], v[152:155], v[186:189], v[84:87]
	v_mfma_f32_16x16x32_bf16 v[88:91], v[144:147], v[234:237], v[88:91]
	v_mfma_f32_16x16x32_bf16 v[48:51], v[152:155], v[234:237], v[48:51]
	s_setprio 0
	s_setprio 1
	v_mfma_f32_16x16x32_bf16 v[104:107], v[148:151], v[164:167], v[104:107]
	v_mfma_f32_16x16x32_bf16 v[68:71], v[156:159], v[164:167], v[68:71]
	v_mfma_f32_16x16x32_bf16 v[100:103], v[148:151], v[172:175], v[100:103]
	v_mfma_f32_16x16x32_bf16 v[52:55], v[156:159], v[172:175], v[52:55]
	v_mfma_f32_16x16x32_bf16 v[96:99], v[148:151], v[230:233], v[96:99]
	v_mfma_f32_16x16x32_bf16 v[84:87], v[156:159], v[230:233], v[84:87]
	v_mfma_f32_16x16x32_bf16 v[88:91], v[148:151], v[238:241], v[88:91]
	v_mfma_f32_16x16x32_bf16 v[48:51], v[156:159], v[238:241], v[48:51]
	s_setprio 0
	s_barrier
; #define PG8_STAGE(bufoff, gbase, voff) do { _Pragma("unroll") for (int _i = 0; _i < 2; ++_i) \
;         __builtin_amdgcn_global_load_lds((const unsigned*)((const char*)(gbase) + (voff)[_i]), (PG8_LAS unsigned*)(lds + (bufoff) + ldsw + _i * 8192), 16, 0, 0); } while (0)
; #define PG8_LDA(dst, b, h) do { _Pragma("unroll") for (int m = 0; m < 4; ++m) _Pragma("unroll") for (int k = 0; k < 2; ++k) dst[m][k] = *(const PG8_LAS bf16x8*)(lds + PG8_SA(b, h) + aoff + m * 2048 + k * 1024); } while (0)
; #define PG8_MMA(ai, bj, At, Bt) do { __builtin_amdgcn_s_setprio(1); _Pragma("unroll") for (int m = 0; m < 4; ++m) _Pragma("unroll") for (int n = 0; n < 2; ++n) _Pragma("unroll") for (int k = 0; k < 2; ++k) \
;         acc[ai][bj][m][n] = __builtin_amdgcn_mfma_f32_16x16x32_bf16(Bt[n][k], At[m][k], acc[ai][bj][m][n], 0, 0, 0); __builtin_amdgcn_s_setprio(0); } while (0)
; #define PG8_WAIT_V(n) asm volatile("s_waitcnt vmcnt(" #n ")" ::: "memory")
; #define PG8_WAIT_L(n) asm volatile("s_waitcnt lgkmcnt(" #n ")" ::: "memory")
; #define PG8_BAR __builtin_amdgcn_s_barrier()
; #define PG8_SCHED __builtin_amdgcn_sched_barrier(0)
; template <class Epi, class Sched, bool ALIGN_EPI = false, bool SP2 = false>
; __device__ __forceinline__ void gemm_phase(PG8_LAS unsigned char* lds, const Gemm g, const Sched& S, const Epi& E) {
;     ...
;             PG8_LDA(At, 1, 1); PG8_STAGE(PG8_SB(1, 0), b3, voffB); PG8_STAGE(PG8_SB(1, 1), b3 + hstepB, voffB); PG8_STAGE(PG8_SA(1, 0), a3, voffA);
;             PG8_WAIT_V(8); PG8_WAIT_L(0); PG8_BAR; PG8_MMA(1, 0, At, B0); PG8_MMA(1, 1, At, B1); PG8_BAR; PG8_SCHED;
;     ...
;         if constexpr (ALIGN_EPI) { if (wr == 0) PG8_BAR; }
	s_add_i32 s60, s81, s66
	v_lshl_add_u64 v[242:243], v[242:243], 0, s[36:37]
	s_mov_b32 m0, s60
	ds_read_b128 v[160:163], v228 offset:49152
	ds_read_b128 v[164:167], v228 offset:50176
	ds_read_b128 v[168:171], v228 offset:51200
	ds_read_b128 v[172:175], v228 offset:52224
	ds_read_b128 v[186:189], v228 offset:53248
	ds_read_b128 v[230:233], v228 offset:54272
	ds_read_b128 v[234:237], v228 offset:55296
	ds_read_b128 v[238:241], v228 offset:56320
	global_load_lds_dwordx4 v[242:243], off
	s_add_i32 m0, s60, 0x2000
	s_add_u32 s60, s62, 0x40080
	v_lshl_add_u64 v[242:243], v[244:245], 0, s[36:37]
	s_addc_u32 s61, s63, 0
	s_add_i32 s62, s82, s66
	global_load_lds_dwordx4 v[242:243], off
	v_lshl_add_u64 v[242:243], s[60:61], 0, v[192:193]
	s_mov_b32 m0, s62
	s_nop 0
	global_load_lds_dwordx4 v[242:243], off
	v_lshl_add_u64 v[242:243], s[60:61], 0, v[180:181]
	s_add_i32 m0, s62, 0x2000
	s_nop 0
	global_load_lds_dwordx4 v[242:243], off
	v_lshl_add_u64 v[242:243], v[246:247], 0, s[36:37]
	s_mov_b32 m0, s70
	s_nop 0
	global_load_lds_dwordx4 v[242:243], off
	v_lshl_add_u64 v[242:243], v[248:249], 0, s[36:37]
	s_mov_b32 m0, s71
	s_nop 0
	global_load_lds_dwordx4 v[242:243], off
	s_waitcnt vmcnt(8)
	s_waitcnt lgkmcnt(0)
	s_barrier
	s_setprio 1
	s_waitcnt lgkmcnt(0)
	v_mfma_f32_16x16x32_bf16 v[36:39], v[116:119], v[160:163], v[36:39]
	v_mfma_f32_16x16x32_bf16 v[12:15], v[136:139], v[160:163], v[12:15]
	v_mfma_f32_16x16x32_bf16 v[24:27], v[116:119], v[168:171], v[24:27]
	v_mfma_f32_16x16x32_bf16 v[4:7], v[136:139], v[168:171], v[4:7]
	v_mfma_f32_16x16x32_bf16 v[64:67], v[116:119], v[186:189], v[64:67]
	v_mfma_f32_16x16x32_bf16 v[32:35], v[136:139], v[186:189], v[32:35]
	v_mfma_f32_16x16x32_bf16 v[76:79], v[116:119], v[234:237], v[76:79]
	v_mfma_f32_16x16x32_bf16 v[40:43], v[136:139], v[234:237], v[40:43]
	s_setprio 0
	s_setprio 1
	v_mfma_f32_16x16x32_bf16 v[36:39], v[132:135], v[164:167], v[36:39]
	v_mfma_f32_16x16x32_bf16 v[12:15], v[140:143], v[164:167], v[12:15]
	v_mfma_f32_16x16x32_bf16 v[24:27], v[132:135], v[172:175], v[24:27]
	v_mfma_f32_16x16x32_bf16 v[4:7], v[140:143], v[172:175], v[4:7]
	v_mfma_f32_16x16x32_bf16 v[64:67], v[132:135], v[230:233], v[64:67]
	v_mfma_f32_16x16x32_bf16 v[32:35], v[140:143], v[230:233], v[32:35]
	v_mfma_f32_16x16x32_bf16 v[76:79], v[132:135], v[238:241], v[76:79]
	v_mfma_f32_16x16x32_bf16 v[40:43], v[140:143], v[238:241], v[40:43]
	s_setprio 0
	s_setprio 1
	v_mfma_f32_16x16x32_bf16 v[20:23], v[144:147], v[160:163], v[20:23]
	v_mfma_f32_16x16x32_bf16 v[8:11], v[152:155], v[160:163], v[8:11]
	v_mfma_f32_16x16x32_bf16 v[16:19], v[144:147], v[168:171], v[16:19]
	v_mfma_f32_16x16x32_bf16 v[0:3], v[152:155], v[168:171], v[0:3]
	v_mfma_f32_16x16x32_bf16 v[60:63], v[144:147], v[186:189], v[60:63]
	v_mfma_f32_16x16x32_bf16 v[28:31], v[152:155], v[186:189], v[28:31]
	v_mfma_f32_16x16x32_bf16 v[72:75], v[144:147], v[234:237], v[72:75]
	v_mfma_f32_16x16x32_bf16 v[44:47], v[152:155], v[234:237], v[44:47]
	s_setprio 0
	s_setprio 1
	v_mfma_f32_16x16x32_bf16 v[20:23], v[148:151], v[164:167], v[20:23]
	v_mfma_f32_16x16x32_bf16 v[8:11], v[156:159], v[164:167], v[8:11]
	v_mfma_f32_16x16x32_bf16 v[16:19], v[148:151], v[172:175], v[16:19]
	v_mfma_f32_16x16x32_bf16 v[0:3], v[156:159], v[172:175], v[0:3]
	v_mfma_f32_16x16x32_bf16 v[60:63], v[148:151], v[230:233], v[60:63]
	v_mfma_f32_16x16x32_bf16 v[28:31], v[156:159], v[230:233], v[28:31]
	v_mfma_f32_16x16x32_bf16 v[72:75], v[148:151], v[238:241], v[72:75]
	v_mfma_f32_16x16x32_bf16 v[44:47], v[156:159], v[238:241], v[44:47]
	s_setprio 0
	s_barrier
	s_add_i32 s80, s80, 2
	s_add_u32 s78, s78, 0x100
	s_addc_u32 s79, s79, 0
	s_cmp_gt_u32 s80, 13
	s_mov_b64 s[60:61], s[56:57]
	s_cbranch_scc0 .LBB0_77
	s_and_b64 vcc, exec, s[12:13]
	s_cbranch_vccz .LBB0_80
	s_barrier

; #define PG8_STAGE(bufoff, gbase, voff) do { _Pragma("unroll") for (int _i = 0; _i < 2; ++_i) \
;         __builtin_amdgcn_global_load_lds((const unsigned*)((const char*)(gbase) + (voff)[_i]), (PG8_LAS unsigned*)(lds + (bufoff) + ldsw + _i * 8192), 16, 0, 0); } while (0)
; #define PG8_LDA(dst, b, h) do { _Pragma("unroll") for (int m = 0; m < 4; ++m) _Pragma("unroll") for (int k = 0; k < 2; ++k) dst[m][k] = *(const PG8_LAS bf16x8*)(lds + PG8_SA(b, h) + aoff + m * 2048 + k * 1024); } while (0)
; #define PG8_LDB(dst, b, h) do { _Pragma("unroll") for (int n = 0; n < 2; ++n) _Pragma("unroll") for (int k = 0; k < 2; ++k) dst[n][k] = *(const PG8_LAS bf16x8*)(lds + PG8_SB(b, h) + boff + n * 2048 + k * 1024); } while (0)
; #define PG8_MMA(ai, bj, At, Bt) do { __builtin_amdgcn_s_setprio(1); _Pragma("unroll") for (int m = 0; m < 4; ++m) _Pragma("unroll") for (int n = 0; n < 2; ++n) _Pragma("unroll") for (int k = 0; k < 2; ++k) \
;         acc[ai][bj][m][n] = __builtin_amdgcn_mfma_f32_16x16x32_bf16(Bt[n][k], At[m][k], acc[ai][bj][m][n], 0, 0, 0); __builtin_amdgcn_s_setprio(0); } while (0)
; #define PG8_WAIT_V(n) asm volatile("s_waitcnt vmcnt(" #n ")" ::: "memory")
; #define PG8_WAIT_L(n) asm volatile("s_waitcnt lgkmcnt(" #n ")" ::: "memory")
; #define PG8_BAR __builtin_amdgcn_s_barrier()
; #define PG8_SCHED __builtin_amdgcn_sched_barrier(0)
; template <class Epi, class Sched, bool ALIGN_EPI = false, bool SP2 = false>
; __device__ __forceinline__ void gemm_phase(PG8_LAS unsigned char* lds, const Gemm g, const Sched& S, const Epi& E) {
;     ...
;             if constexpr (SP2) {
;             PG8_LDB(B0, 0, 0); PG8_LDB(B1, 0, 1); PG8_SCHED; PG8_LDA(At, 0, 0); PG8_STAGE(PG8_SA(1, 1), a1 + hstep, voffA);
;             PG8_WAIT_V(8); PG8_WAIT_L(0); PG8_BAR; PG8_MMA(0, 0, At, B0); PG8_MMA(0, 1, At, B1); PG8_BAR; PG8_SCHED;
;             PG8_LDA(At, 0, 1); PG8_STAGE(PG8_SB(0, 0), b2, voffB); PG8_STAGE(PG8_SB(0, 1), b2 + hstepB, voffB); PG8_STAGE(PG8_SA(0, 0), a2, voffA);
.LBB0_128:
	s_add_u32 s22, s20, 0xfffc0080
	s_addc_u32 s23, s21, -1
	s_add_i32 s58, 0, 0x10000
	s_cmp_eq_u32 s57, 12
	s_cselect_b32 s25, s15, s23
	s_cselect_b32 s24, s53, s22
	s_cselect_b32 s23, s13, s56
	s_cselect_b32 s22, s54, s55
	s_add_i32 s60, 0, 0x14000
	v_add_u32_e32 v140, s58, v169
	v_add_u32_e32 v166, s60, v169
	ds_read_b128 v[112:115], v140
	ds_read_b128 v[124:127], v140 offset:1024
	ds_read_b128 v[128:131], v140 offset:2048
	ds_read_b128 v[140:143], v140 offset:3072
	ds_read_b128 v[154:157], v166
	ds_read_b128 v[158:161], v166 offset:1024
	ds_read_b128 v[162:165], v166 offset:2048
	ds_read_b128 v[172:175], v166 offset:3072
	v_lshl_add_u64 v[166:167], s[20:21], 0, v[152:153]
	s_add_i32 m0, s43, 0xc000
	ds_read_b128 v[176:179], v171
	ds_read_b128 v[180:183], v171 offset:1024
	ds_read_b128 v[184:187], v171 offset:2048
	ds_read_b128 v[188:191], v171 offset:3072
	ds_read_b128 v[206:209], v171 offset:4096
	ds_read_b128 v[210:213], v171 offset:5120
	ds_read_b128 v[214:217], v171 offset:6144
	ds_read_b128 v[224:227], v171 offset:7168
	global_load_lds_dwordx4 v[166:167], off
	v_lshl_add_u64 v[166:167], s[20:21], 0, v[150:151]
	s_add_i32 m0, s43, 0xe000
	s_nop 0
	global_load_lds_dwordx4 v[166:167], off
	s_waitcnt vmcnt(8)
	s_waitcnt lgkmcnt(0)
	s_barrier
	s_setprio 1
	s_waitcnt lgkmcnt(0)
	v_mfma_f32_16x16x32_bf16 v[136:139], v[112:115], v[176:179], v[136:139]
	v_mfma_f32_16x16x32_bf16 v[132:135], v[128:131], v[176:179], v[132:135]
	v_mfma_f32_16x16x32_bf16 v[108:111], v[112:115], v[184:187], v[108:111]
	v_mfma_f32_16x16x32_bf16 v[104:107], v[128:131], v[184:187], v[104:107]
	v_mfma_f32_16x16x32_bf16 v[92:95], v[112:115], v[206:209], v[92:95]
	v_mfma_f32_16x16x32_bf16 v[88:91], v[128:131], v[206:209], v[88:91]
	v_mfma_f32_16x16x32_bf16 v[76:79], v[112:115], v[214:217], v[76:79]
	v_mfma_f32_16x16x32_bf16 v[72:75], v[128:131], v[214:217], v[72:75]
	s_setprio 0
	s_setprio 1
	v_mfma_f32_16x16x32_bf16 v[136:139], v[124:127], v[180:183], v[136:139]
	v_mfma_f32_16x16x32_bf16 v[132:135], v[140:143], v[180:183], v[132:135]
	v_mfma_f32_16x16x32_bf16 v[108:111], v[124:127], v[188:191], v[108:111]
	v_mfma_f32_16x16x32_bf16 v[104:107], v[140:143], v[188:191], v[104:107]
	v_mfma_f32_16x16x32_bf16 v[92:95], v[124:127], v[210:213], v[92:95]
	v_mfma_f32_16x16x32_bf16 v[88:91], v[140:143], v[210:213], v[88:91]
	v_mfma_f32_16x16x32_bf16 v[76:79], v[124:127], v[224:227], v[76:79]
	v_mfma_f32_16x16x32_bf16 v[72:75], v[140:143], v[224:227], v[72:75]
	s_setprio 0
	s_setprio 1
	v_mfma_f32_16x16x32_bf16 v[120:123], v[154:157], v[176:179], v[120:123]
	v_mfma_f32_16x16x32_bf16 v[116:119], v[162:165], v[176:179], v[116:119]
	v_mfma_f32_16x16x32_bf16 v[100:103], v[154:157], v[184:187], v[100:103]
	v_mfma_f32_16x16x32_bf16 v[96:99], v[162:165], v[184:187], v[96:99]
	v_mfma_f32_16x16x32_bf16 v[84:87], v[154:157], v[206:209], v[84:87]
	v_mfma_f32_16x16x32_bf16 v[80:83], v[162:165], v[206:209], v[80:83]
	v_mfma_f32_16x16x32_bf16 v[68:71], v[154:157], v[214:217], v[68:71]
	v_mfma_f32_16x16x32_bf16 v[64:67], v[162:165], v[214:217], v[64:67]
	s_setprio 0
	s_setprio 1
	v_mfma_f32_16x16x32_bf16 v[120:123], v[158:161], v[180:183], v[120:123]
	v_mfma_f32_16x16x32_bf16 v[116:119], v[172:175], v[180:183], v[116:119]
	v_mfma_f32_16x16x32_bf16 v[100:103], v[158:161], v[188:191], v[100:103]
	v_mfma_f32_16x16x32_bf16 v[96:99], v[172:175], v[188:191], v[96:99]
	v_mfma_f32_16x16x32_bf16 v[84:87], v[158:161], v[210:213], v[84:87]
	v_mfma_f32_16x16x32_bf16 v[80:83], v[172:175], v[210:213], v[80:83]
	v_mfma_f32_16x16x32_bf16 v[68:71], v[158:161], v[224:227], v[68:71]
	v_mfma_f32_16x16x32_bf16 v[64:67], v[172:175], v[224:227], v[64:67]
	s_setprio 0
	s_barrier
	s_add_i32 s58, s58, s42
	v_lshl_add_u64 v[166:167], s[22:23], 0, v[192:193]
	s_mov_b32 m0, s58
	ds_read_b128 v[176:179], v171 offset:16384
	ds_read_b128 v[180:183], v171 offset:17408
	ds_read_b128 v[184:187], v171 offset:18432
	ds_read_b128 v[188:191], v171 offset:19456
	ds_read_b128 v[206:209], v171 offset:20480
	ds_read_b128 v[210:213], v171 offset:21504
	ds_read_b128 v[214:217], v171 offset:22528
	ds_read_b128 v[224:227], v171 offset:23552
	global_load_lds_dwordx4 v[166:167], off
	s_add_i32 m0, s58, 0x2000
	s_add_u32 s58, s22, 0x10000
	v_lshl_add_u64 v[228:229], s[22:23], 0, v[144:145]
	s_addc_u32 s59, s23, 0
	s_add_i32 s60, s60, s42
	global_load_lds_dwordx4 v[228:229], off
	v_lshl_add_u64 v[230:231], s[58:59], 0, v[192:193]
	s_mov_b32 m0, s60
	v_lshl_add_u64 v[232:233], s[24:25], 0, v[146:147]
	global_load_lds_dwordx4 v[230:231], off
	v_lshl_add_u64 v[230:231], s[58:59], 0, v[144:145]
	s_add_i32 m0, s60, 0x2000
	s_nop 0
	global_load_lds_dwordx4 v[230:231], off
	v_lshl_add_u64 v[230:231], s[24:25], 0, v[148:149]
	s_mov_b32 m0, s43
	s_nop 0
	global_load_lds_dwordx4 v[230:231], off
	s_mov_b32 m0, s44
	s_nop 0
	global_load_lds_dwordx4 v[232:233], off
	s_waitcnt vmcnt(8)
	s_waitcnt lgkmcnt(0)
	s_barrier
; #define PG8_STAGE(bufoff, gbase, voff) do { _Pragma("unroll") for (int _i = 0; _i < 2; ++_i) \
;         __builtin_amdgcn_global_load_lds((const unsigned*)((const char*)(gbase) + (voff)[_i]), (PG8_LAS unsigned*)(lds + (bufoff) + ldsw + _i * 8192), 16, 0, 0); } while (0)
; #define PG8_LDA(dst, b, h) do { _Pragma("unroll") for (int m = 0; m < 4; ++m) _Pragma("unroll") for (int k = 0; k < 2; ++k) dst[m][k] = *(const PG8_LAS bf16x8*)(lds + PG8_SA(b, h) + aoff + m * 2048 + k * 1024); } while (0)
; #define PG8_LDB(dst, b, h) do { _Pragma("unroll") for (int n = 0; n < 2; ++n) _Pragma("unroll") for (int k = 0; k < 2; ++k) dst[n][k] = *(const PG8_LAS bf16x8*)(lds + PG8_SB(b, h) + boff + n * 2048 + k * 1024); } while (0)
; #define PG8_MMA(ai, bj, At, Bt) do { __builtin_amdgcn_s_setprio(1); _Pragma("unroll") for (int m = 0; m < 4; ++m) _Pragma("unroll") for (int n = 0; n < 2; ++n) _Pragma("unroll") for (int k = 0; k < 2; ++k) \
;         acc[ai][bj][m][n] = __builtin_amdgcn_mfma_f32_16x16x32_bf16(Bt[n][k], At[m][k], acc[ai][bj][m][n], 0, 0, 0); __builtin_amdgcn_s_setprio(0); } while (0)
; #define PG8_WAIT_V(n) asm volatile("s_waitcnt vmcnt(" #n ")" ::: "memory")
; #define PG8_WAIT_L(n) asm volatile("s_waitcnt lgkmcnt(" #n ")" ::: "memory")
; #define PG8_BAR __builtin_amdgcn_s_barrier()
; #define PG8_SCHED __builtin_amdgcn_sched_barrier(0)
; template <class Epi, class Sched, bool ALIGN_EPI = false, bool SP2 = false>
; __device__ __forceinline__ void gemm_phase(PG8_LAS unsigned char* lds, const Gemm g, const Sched& S, const Epi& E) {
;     ...
;             PG8_WAIT_V(8); PG8_WAIT_L(0); PG8_BAR; PG8_MMA(1, 0, At, B0); PG8_MMA(1, 1, At, B1); PG8_BAR; PG8_SCHED;
;             PG8_LDB(B0, 1, 0); PG8_LDB(B1, 1, 1); PG8_SCHED; PG8_LDA(At, 1, 0); PG8_STAGE(PG8_SA(0, 1), a2 + hstep, voffA);
;             PG8_WAIT_V(8); PG8_WAIT_L(0); PG8_BAR; PG8_MMA(0, 0, At, B0); PG8_MMA(0, 1, At, B1); PG8_BAR; PG8_SCHED;
	s_setprio 1
	s_waitcnt lgkmcnt(0)
	v_mfma_f32_16x16x32_bf16 v[60:63], v[112:115], v[176:179], v[60:63]
	v_mfma_f32_16x16x32_bf16 v[56:59], v[128:131], v[176:179], v[56:59]
	v_mfma_f32_16x16x32_bf16 v[44:47], v[112:115], v[184:187], v[44:47]
	v_mfma_f32_16x16x32_bf16 v[40:43], v[128:131], v[184:187], v[40:43]
	v_mfma_f32_16x16x32_bf16 v[28:31], v[112:115], v[206:209], v[28:31]
	v_mfma_f32_16x16x32_bf16 v[24:27], v[128:131], v[206:209], v[24:27]
	v_mfma_f32_16x16x32_bf16 v[12:15], v[112:115], v[214:217], v[12:15]
	v_mfma_f32_16x16x32_bf16 v[8:11], v[128:131], v[214:217], v[8:11]
	s_setprio 0
	s_setprio 1
	v_mfma_f32_16x16x32_bf16 v[60:63], v[124:127], v[180:183], v[60:63]
	v_mfma_f32_16x16x32_bf16 v[56:59], v[140:143], v[180:183], v[56:59]
	v_mfma_f32_16x16x32_bf16 v[44:47], v[124:127], v[188:191], v[44:47]
	v_mfma_f32_16x16x32_bf16 v[40:43], v[140:143], v[188:191], v[40:43]
	v_mfma_f32_16x16x32_bf16 v[28:31], v[124:127], v[210:213], v[28:31]
	v_mfma_f32_16x16x32_bf16 v[24:27], v[140:143], v[210:213], v[24:27]
	v_mfma_f32_16x16x32_bf16 v[12:15], v[124:127], v[224:227], v[12:15]
	v_mfma_f32_16x16x32_bf16 v[8:11], v[140:143], v[224:227], v[8:11]
	s_setprio 0
	s_setprio 1
	v_mfma_f32_16x16x32_bf16 v[52:55], v[154:157], v[176:179], v[52:55]
	v_mfma_f32_16x16x32_bf16 v[48:51], v[162:165], v[176:179], v[48:51]
	v_mfma_f32_16x16x32_bf16 v[36:39], v[154:157], v[184:187], v[36:39]
	v_mfma_f32_16x16x32_bf16 v[32:35], v[162:165], v[184:187], v[32:35]
	v_mfma_f32_16x16x32_bf16 v[20:23], v[154:157], v[206:209], v[20:23]
	v_mfma_f32_16x16x32_bf16 v[16:19], v[162:165], v[206:209], v[16:19]
	v_mfma_f32_16x16x32_bf16 v[4:7], v[154:157], v[214:217], v[4:7]
	v_mfma_f32_16x16x32_bf16 v[0:3], v[162:165], v[214:217], v[0:3]
	s_setprio 0
	s_setprio 1
	v_mfma_f32_16x16x32_bf16 v[52:55], v[158:161], v[180:183], v[52:55]
	v_mfma_f32_16x16x32_bf16 v[48:51], v[172:175], v[180:183], v[48:51]
	v_mfma_f32_16x16x32_bf16 v[36:39], v[158:161], v[188:191], v[36:39]
	v_mfma_f32_16x16x32_bf16 v[32:35], v[172:175], v[188:191], v[32:35]
	v_mfma_f32_16x16x32_bf16 v[20:23], v[158:161], v[210:213], v[20:23]
	v_mfma_f32_16x16x32_bf16 v[16:19], v[172:175], v[210:213], v[16:19]
	v_mfma_f32_16x16x32_bf16 v[4:7], v[158:161], v[224:227], v[4:7]
	v_mfma_f32_16x16x32_bf16 v[0:3], v[172:175], v[224:227], v[0:3]
	s_setprio 0
	s_barrier
	s_add_i32 s58, 0, 0x18000
	s_add_i32 s59, 0, 0x1c000
	v_add_u32_e32 v140, s58, v169
	v_add_u32_e32 v172, s59, v169
	ds_read_b128 v[112:115], v140
	ds_read_b128 v[124:127], v140 offset:1024
	ds_read_b128 v[128:131], v140 offset:2048
	ds_read_b128 v[140:143], v140 offset:3072
	ds_read_b128 v[154:157], v172
	ds_read_b128 v[158:161], v172 offset:1024
	ds_read_b128 v[162:165], v172 offset:2048
	ds_read_b128 v[172:175], v172 offset:3072
	s_add_u32 s24, s24, 0x40000
	s_addc_u32 s25, s25, 0
	s_mov_b32 m0, s45
	v_lshl_add_u64 v[234:235], s[24:25], 0, v[148:149]
	ds_read_b128 v[176:179], v171 offset:32768
	ds_read_b128 v[180:183], v171 offset:33792
	ds_read_b128 v[184:187], v171 offset:34816
	ds_read_b128 v[188:191], v171 offset:35840
	ds_read_b128 v[206:209], v171 offset:36864
	ds_read_b128 v[210:213], v171 offset:37888
	ds_read_b128 v[214:217], v171 offset:38912
	ds_read_b128 v[224:227], v171 offset:39936
	global_load_lds_dwordx4 v[234:235], off
	v_lshl_add_u64 v[234:235], s[24:25], 0, v[146:147]
	s_mov_b32 m0, s46
	s_nop 0
	global_load_lds_dwordx4 v[234:235], off
	s_waitcnt vmcnt(8)
	s_waitcnt lgkmcnt(0)
	s_barrier
	s_setprio 1
	s_waitcnt lgkmcnt(0)
	v_mfma_f32_16x16x32_bf16 v[136:139], v[112:115], v[176:179], v[136:139]
	v_mfma_f32_16x16x32_bf16 v[132:135], v[128:131], v[176:179], v[132:135]
	v_mfma_f32_16x16x32_bf16 v[108:111], v[112:115], v[184:187], v[108:111]
	v_mfma_f32_16x16x32_bf16 v[104:107], v[128:131], v[184:187], v[104:107]
	v_mfma_f32_16x16x32_bf16 v[92:95], v[112:115], v[206:209], v[92:95]
	v_mfma_f32_16x16x32_bf16 v[88:91], v[128:131], v[206:209], v[88:91]
	v_mfma_f32_16x16x32_bf16 v[76:79], v[112:115], v[214:217], v[76:79]
	v_mfma_f32_16x16x32_bf16 v[72:75], v[128:131], v[214:217], v[72:75]
	s_setprio 0
	s_setprio 1
	v_mfma_f32_16x16x32_bf16 v[136:139], v[124:127], v[180:183], v[136:139]
	v_mfma_f32_16x16x32_bf16 v[132:135], v[140:143], v[180:183], v[132:135]
	v_mfma_f32_16x16x32_bf16 v[108:111], v[124:127], v[188:191], v[108:111]
	v_mfma_f32_16x16x32_bf16 v[104:107], v[140:143], v[188:191], v[104:107]
	v_mfma_f32_16x16x32_bf16 v[92:95], v[124:127], v[210:213], v[92:95]
	v_mfma_f32_16x16x32_bf16 v[88:91], v[140:143], v[210:213], v[88:91]
	v_mfma_f32_16x16x32_bf16 v[76:79], v[124:127], v[224:227], v[76:79]
	v_mfma_f32_16x16x32_bf16 v[72:75], v[140:143], v[224:227], v[72:75]
	s_setprio 0
	s_setprio 1
	v_mfma_f32_16x16x32_bf16 v[120:123], v[154:157], v[176:179], v[120:123]
	v_mfma_f32_16x16x32_bf16 v[116:119], v[162:165], v[176:179], v[116:119]
	v_mfma_f32_16x16x32_bf16 v[100:103], v[154:157], v[184:187], v[100:103]
	v_mfma_f32_16x16x32_bf16 v[96:99], v[162:165], v[184:187], v[96:99]
	v_mfma_f32_16x16x32_bf16 v[84:87], v[154:157], v[206:209], v[84:87]
	v_mfma_f32_16x16x32_bf16 v[80:83], v[162:165], v[206:209], v[80:83]
	v_mfma_f32_16x16x32_bf16 v[68:71], v[154:157], v[214:217], v[68:71]
	v_mfma_f32_16x16x32_bf16 v[64:67], v[162:165], v[214:217], v[64:67]
	s_setprio 0
	s_setprio 1
	v_mfma_f32_16x16x32_bf16 v[120:123], v[158:161], v[180:183], v[120:123]
	v_mfma_f32_16x16x32_bf16 v[116:119], v[172:175], v[180:183], v[116:119]
	v_mfma_f32_16x16x32_bf16 v[100:103], v[158:161], v[188:191], v[100:103]
	v_mfma_f32_16x16x32_bf16 v[96:99], v[172:175], v[188:191], v[96:99]
	v_mfma_f32_16x16x32_bf16 v[84:87], v[158:161], v[210:213], v[84:87]
	v_mfma_f32_16x16x32_bf16 v[80:83], v[172:175], v[210:213], v[80:83]
	v_mfma_f32_16x16x32_bf16 v[68:71], v[158:161], v[224:227], v[68:71]
	v_mfma_f32_16x16x32_bf16 v[64:67], v[172:175], v[224:227], v[64:67]
	s_setprio 0
	s_barrier
; #define PG8_STAGE(bufoff, gbase, voff) do { _Pragma("unroll") for (int _i = 0; _i < 2; ++_i) \
;         __builtin_amdgcn_global_load_lds((const unsigned*)((const char*)(gbase) + (voff)[_i]), (PG8_LAS unsigned*)(lds + (bufoff) + ldsw + _i * 8192), 16, 0, 0); } while (0)
; #define PG8_LDA(dst, b, h) do { _Pragma("unroll") for (int m = 0; m < 4; ++m) _Pragma("unroll") for (int k = 0; k < 2; ++k) dst[m][k] = *(const PG8_LAS bf16x8*)(lds + PG8_SA(b, h) + aoff + m * 2048 + k * 1024); } while (0)
; #define PG8_MMA(ai, bj, At, Bt) do { __builtin_amdgcn_s_setprio(1); _Pragma("unroll") for (int m = 0; m < 4; ++m) _Pragma("unroll") for (int n = 0; n < 2; ++n) _Pragma("unroll") for (int k = 0; k < 2; ++k) \
;         acc[ai][bj][m][n] = __builtin_amdgcn_mfma_f32_16x16x32_bf16(Bt[n][k], At[m][k], acc[ai][bj][m][n], 0, 0, 0); __builtin_amdgcn_s_setprio(0); } while (0)
; #define PG8_WAIT_V(n) asm volatile("s_waitcnt vmcnt(" #n ")" ::: "memory")
; #define PG8_WAIT_L(n) asm volatile("s_waitcnt lgkmcnt(" #n ")" ::: "memory")
; #define PG8_BAR __builtin_amdgcn_s_barrier()
; #define PG8_SCHED __builtin_amdgcn_sched_barrier(0)
; template <class Epi, class Sched, bool ALIGN_EPI = false, bool SP2 = false>
; __device__ __forceinline__ void gemm_phase(PG8_LAS unsigned char* lds, const Gemm g, const Sched& S, const Epi& E) {
;     ...
;             PG8_LDA(At, 1, 1); PG8_STAGE(PG8_SB(1, 0), b3, voffB); PG8_STAGE(PG8_SB(1, 1), b3 + hstepB, voffB); PG8_STAGE(PG8_SA(1, 0), a3, voffA);
;             PG8_WAIT_V(8); PG8_WAIT_L(0); PG8_BAR; PG8_MMA(1, 0, At, B0); PG8_MMA(1, 1, At, B1); PG8_BAR; PG8_SCHED;
;     ...
;         if constexpr (ALIGN_EPI) { if (wr == 0) PG8_BAR; }
	s_add_i32 s24, s58, s42
	v_lshl_add_u64 v[166:167], v[166:167], 0, s[36:37]
	s_mov_b32 m0, s24
	ds_read_b128 v[176:179], v171 offset:49152
	ds_read_b128 v[180:183], v171 offset:50176
	ds_read_b128 v[184:187], v171 offset:51200
	ds_read_b128 v[188:191], v171 offset:52224
	ds_read_b128 v[206:209], v171 offset:53248
	ds_read_b128 v[210:213], v171 offset:54272
	ds_read_b128 v[214:217], v171 offset:55296
	ds_read_b128 v[224:227], v171 offset:56320
	global_load_lds_dwordx4 v[166:167], off
	s_add_i32 m0, s24, 0x2000
	s_add_u32 s22, s22, 0x10080
	v_lshl_add_u64 v[166:167], v[228:229], 0, s[36:37]
	s_addc_u32 s23, s23, 0
	s_add_i32 s24, s59, s42
	global_load_lds_dwordx4 v[166:167], off
	v_lshl_add_u64 v[166:167], s[22:23], 0, v[192:193]
	s_mov_b32 m0, s24
	s_nop 0
	global_load_lds_dwordx4 v[166:167], off
	v_lshl_add_u64 v[166:167], s[22:23], 0, v[144:145]
	s_add_i32 m0, s24, 0x2000
	s_nop 0
	global_load_lds_dwordx4 v[166:167], off
	v_lshl_add_u64 v[166:167], v[230:231], 0, s[36:37]
	s_mov_b32 m0, s48
	s_nop 0
	global_load_lds_dwordx4 v[166:167], off
	v_lshl_add_u64 v[166:167], v[232:233], 0, s[36:37]
	s_mov_b32 m0, s49
	s_nop 0
	global_load_lds_dwordx4 v[166:167], off
	s_waitcnt vmcnt(8)
	s_waitcnt lgkmcnt(0)
	s_barrier
	s_setprio 1
	s_waitcnt lgkmcnt(0)
	v_mfma_f32_16x16x32_bf16 v[60:63], v[112:115], v[176:179], v[60:63]
	v_mfma_f32_16x16x32_bf16 v[56:59], v[128:131], v[176:179], v[56:59]
	v_mfma_f32_16x16x32_bf16 v[44:47], v[112:115], v[184:187], v[44:47]
	v_mfma_f32_16x16x32_bf16 v[40:43], v[128:131], v[184:187], v[40:43]
	v_mfma_f32_16x16x32_bf16 v[28:31], v[112:115], v[206:209], v[28:31]
	v_mfma_f32_16x16x32_bf16 v[24:27], v[128:131], v[206:209], v[24:27]
	v_mfma_f32_16x16x32_bf16 v[12:15], v[112:115], v[214:217], v[12:15]
	v_mfma_f32_16x16x32_bf16 v[8:11], v[128:131], v[214:217], v[8:11]
	s_setprio 0
	s_setprio 1
	v_mfma_f32_16x16x32_bf16 v[60:63], v[124:127], v[180:183], v[60:63]
	v_mfma_f32_16x16x32_bf16 v[56:59], v[140:143], v[180:183], v[56:59]
	v_mfma_f32_16x16x32_bf16 v[44:47], v[124:127], v[188:191], v[44:47]
	v_mfma_f32_16x16x32_bf16 v[40:43], v[140:143], v[188:191], v[40:43]
	v_mfma_f32_16x16x32_bf16 v[28:31], v[124:127], v[210:213], v[28:31]
	v_mfma_f32_16x16x32_bf16 v[24:27], v[140:143], v[210:213], v[24:27]
	v_mfma_f32_16x16x32_bf16 v[12:15], v[124:127], v[224:227], v[12:15]
	v_mfma_f32_16x16x32_bf16 v[8:11], v[140:143], v[224:227], v[8:11]
	s_setprio 0
	s_setprio 1
	v_mfma_f32_16x16x32_bf16 v[52:55], v[154:157], v[176:179], v[52:55]
	v_mfma_f32_16x16x32_bf16 v[48:51], v[162:165], v[176:179], v[48:51]
	v_mfma_f32_16x16x32_bf16 v[36:39], v[154:157], v[184:187], v[36:39]
	v_mfma_f32_16x16x32_bf16 v[32:35], v[162:165], v[184:187], v[32:35]
	v_mfma_f32_16x16x32_bf16 v[20:23], v[154:157], v[206:209], v[20:23]
	v_mfma_f32_16x16x32_bf16 v[16:19], v[162:165], v[206:209], v[16:19]
	v_mfma_f32_16x16x32_bf16 v[4:7], v[154:157], v[214:217], v[4:7]
	v_mfma_f32_16x16x32_bf16 v[0:3], v[162:165], v[214:217], v[0:3]
	s_setprio 0
	s_setprio 1
	v_mfma_f32_16x16x32_bf16 v[52:55], v[158:161], v[180:183], v[52:55]
	v_mfma_f32_16x16x32_bf16 v[48:51], v[172:175], v[180:183], v[48:51]
	v_mfma_f32_16x16x32_bf16 v[36:39], v[158:161], v[188:191], v[36:39]
	v_mfma_f32_16x16x32_bf16 v[32:35], v[172:175], v[188:191], v[32:35]
	v_mfma_f32_16x16x32_bf16 v[20:23], v[158:161], v[210:213], v[20:23]
	v_mfma_f32_16x16x32_bf16 v[16:19], v[172:175], v[210:213], v[16:19]
	v_mfma_f32_16x16x32_bf16 v[4:7], v[158:161], v[224:227], v[4:7]
	v_mfma_f32_16x16x32_bf16 v[0:3], v[172:175], v[224:227], v[0:3]
	s_setprio 0
	s_barrier
	s_add_i32 s57, s57, 2
	s_add_u32 s55, s55, 0x100
	s_addc_u32 s56, s56, 0
	s_add_u32 s20, s20, 0x100
	s_addc_u32 s21, s21, 0
	s_cmp_gt_u32 s57, 13
	s_cbranch_scc0 .LBB0_128
	s_and_b64 vcc, exec, s[10:11]
	s_cbranch_vccz .LBB0_131
	s_barrier

; #define PG8_STAGE(bufoff, gbase, voff) do { _Pragma("unroll") for (int _i = 0; _i < 2; ++_i) \
;         __builtin_amdgcn_global_load_lds((const unsigned*)((const char*)(gbase) + (voff)[_i]), (PG8_LAS unsigned*)(lds + (bufoff) + ldsw + _i * 8192), 16, 0, 0); } while (0)
; #define PG8_LDA(dst, b, h) do { _Pragma("unroll") for (int m = 0; m < 4; ++m) _Pragma("unroll") for (int k = 0; k < 2; ++k) dst[m][k] = *(const PG8_LAS bf16x8*)(lds + PG8_SA(b, h) + aoff + m * 2048 + k * 1024); } while (0)
; #define PG8_LDB(dst, b, h) do { _Pragma("unroll") for (int n = 0; n < 2; ++n) _Pragma("unroll") for (int k = 0; k < 2; ++k) dst[n][k] = *(const PG8_LAS bf16x8*)(lds + PG8_SB(b, h) + boff + n * 2048 + k * 1024); } while (0)
; #define PG8_MMA(ai, bj, At, Bt) do { __builtin_amdgcn_s_setprio(1); _Pragma("unroll") for (int m = 0; m < 4; ++m) _Pragma("unroll") for (int n = 0; n < 2; ++n) _Pragma("unroll") for (int k = 0; k < 2; ++k) \
;         acc[ai][bj][m][n] = __builtin_amdgcn_mfma_f32_16x16x32_bf16(Bt[n][k], At[m][k], acc[ai][bj][m][n], 0, 0, 0); __builtin_amdgcn_s_setprio(0); } while (0)
; #define PG8_WAIT_V(n) asm volatile("s_waitcnt vmcnt(" #n ")" ::: "memory")
; #define PG8_WAIT_L(n) asm volatile("s_waitcnt lgkmcnt(" #n ")" ::: "memory")
; #define PG8_BAR __builtin_amdgcn_s_barrier()
; #define PG8_SCHED __builtin_amdgcn_sched_barrier(0)
; template <class Epi, class Sched, bool ALIGN_EPI = false, bool SP2 = false>
; __device__ __forceinline__ void gemm_phase(PG8_LAS unsigned char* lds, const Gemm g, const Sched& S, const Epi& E) {
;     ...
;             if constexpr (SP2) {
;             PG8_LDB(B0, 0, 0); PG8_LDB(B1, 0, 1); PG8_SCHED; PG8_LDA(At, 0, 0); PG8_STAGE(PG8_SA(1, 1), a1 + hstep, voffA);
;             PG8_WAIT_V(8); PG8_WAIT_L(0); PG8_BAR; PG8_MMA(0, 0, At, B0); PG8_MMA(0, 1, At, B1); PG8_BAR; PG8_SCHED;
;             PG8_LDA(At, 0, 1); PG8_STAGE(PG8_SB(0, 0), b2, voffB); PG8_STAGE(PG8_SB(0, 1), b2 + hstepB, voffB); PG8_STAGE(PG8_SA(0, 0), a2, voffA);
.LBB0_304:
	s_add_u32 s22, s20, 0xfffc0080
	s_addc_u32 s23, s21, -1
	s_add_i32 s57, 0, 0x10000
	s_cmp_eq_u32 s56, 12
	s_cselect_b32 s25, s15, s23
	s_cselect_b32 s24, s52, s22
	s_cselect_b32 s23, s13, s55
	s_cselect_b32 s22, s53, s54
	s_add_i32 s60, 0, 0x14000
	v_add_u32_e32 v158, s57, v143
	v_add_u32_e32 v174, s60, v143
	ds_read_b128 v[138:141], v158
	ds_read_b128 v[150:153], v158 offset:1024
	ds_read_b128 v[154:157], v158 offset:2048
	ds_read_b128 v[158:161], v158 offset:3072
	ds_read_b128 v[162:165], v174
	ds_read_b128 v[166:169], v174 offset:1024
	ds_read_b128 v[170:173], v174 offset:2048
	ds_read_b128 v[174:177], v174 offset:3072
	v_lshl_add_u64 v[190:191], s[20:21], 0, v[136:137]
	s_add_i32 m0, s43, 0xc000
	ds_read_b128 v[178:181], v149
	ds_read_b128 v[182:185], v149 offset:1024
	ds_read_b128 v[186:189], v149 offset:2048
	ds_read_b128 v[206:209], v149 offset:3072
	ds_read_b128 v[210:213], v149 offset:4096
	ds_read_b128 v[214:217], v149 offset:5120
	ds_read_b128 v[224:227], v149 offset:6144
	ds_read_b128 v[228:231], v149 offset:7168
	global_load_lds_dwordx4 v[190:191], off
	v_lshl_add_u64 v[190:191], s[20:21], 0, v[134:135]
	s_add_i32 m0, s43, 0xe000
	s_nop 0
	global_load_lds_dwordx4 v[190:191], off
	s_waitcnt vmcnt(8)
	s_waitcnt lgkmcnt(0)
	s_barrier
	s_setprio 1
	s_waitcnt lgkmcnt(0)
	v_mfma_f32_16x16x32_bf16 v[124:127], v[138:141], v[178:181], v[124:127]
	v_mfma_f32_16x16x32_bf16 v[120:123], v[154:157], v[178:181], v[120:123]
	v_mfma_f32_16x16x32_bf16 v[112:115], v[138:141], v[186:189], v[112:115]
	v_mfma_f32_16x16x32_bf16 v[104:107], v[154:157], v[186:189], v[104:107]
	v_mfma_f32_16x16x32_bf16 v[96:99], v[138:141], v[210:213], v[96:99]
	v_mfma_f32_16x16x32_bf16 v[88:91], v[154:157], v[210:213], v[88:91]
	v_mfma_f32_16x16x32_bf16 v[80:83], v[138:141], v[224:227], v[80:83]
	v_mfma_f32_16x16x32_bf16 v[72:75], v[154:157], v[224:227], v[72:75]
	s_setprio 0
	s_setprio 1
	v_mfma_f32_16x16x32_bf16 v[124:127], v[150:153], v[182:185], v[124:127]
	v_mfma_f32_16x16x32_bf16 v[120:123], v[158:161], v[182:185], v[120:123]
	v_mfma_f32_16x16x32_bf16 v[112:115], v[150:153], v[206:209], v[112:115]
	v_mfma_f32_16x16x32_bf16 v[104:107], v[158:161], v[206:209], v[104:107]
	v_mfma_f32_16x16x32_bf16 v[96:99], v[150:153], v[214:217], v[96:99]
	v_mfma_f32_16x16x32_bf16 v[88:91], v[158:161], v[214:217], v[88:91]
	v_mfma_f32_16x16x32_bf16 v[80:83], v[150:153], v[228:231], v[80:83]
	v_mfma_f32_16x16x32_bf16 v[72:75], v[158:161], v[228:231], v[72:75]
	s_setprio 0
	s_setprio 1
	v_mfma_f32_16x16x32_bf16 v[116:119], v[162:165], v[178:181], v[116:119]
	v_mfma_f32_16x16x32_bf16 v[108:111], v[170:173], v[178:181], v[108:111]
	v_mfma_f32_16x16x32_bf16 v[100:103], v[162:165], v[186:189], v[100:103]
	v_mfma_f32_16x16x32_bf16 v[92:95], v[170:173], v[186:189], v[92:95]
	v_mfma_f32_16x16x32_bf16 v[84:87], v[162:165], v[210:213], v[84:87]
	v_mfma_f32_16x16x32_bf16 v[76:79], v[170:173], v[210:213], v[76:79]
	v_mfma_f32_16x16x32_bf16 v[68:71], v[162:165], v[224:227], v[68:71]
	v_mfma_f32_16x16x32_bf16 v[64:67], v[170:173], v[224:227], v[64:67]
	s_setprio 0
	s_setprio 1
	v_mfma_f32_16x16x32_bf16 v[116:119], v[166:169], v[182:185], v[116:119]
	v_mfma_f32_16x16x32_bf16 v[108:111], v[174:177], v[182:185], v[108:111]
	v_mfma_f32_16x16x32_bf16 v[100:103], v[166:169], v[206:209], v[100:103]
	v_mfma_f32_16x16x32_bf16 v[92:95], v[174:177], v[206:209], v[92:95]
	v_mfma_f32_16x16x32_bf16 v[84:87], v[166:169], v[214:217], v[84:87]
	v_mfma_f32_16x16x32_bf16 v[76:79], v[174:177], v[214:217], v[76:79]
	v_mfma_f32_16x16x32_bf16 v[68:71], v[166:169], v[228:231], v[68:71]
	v_mfma_f32_16x16x32_bf16 v[64:67], v[174:177], v[228:231], v[64:67]
	s_setprio 0
	s_barrier
	s_add_i32 s57, s57, s42
	v_lshl_add_u64 v[190:191], s[22:23], 0, v[192:193]
	s_mov_b32 m0, s57
	ds_read_b128 v[178:181], v149 offset:16384
	ds_read_b128 v[182:185], v149 offset:17408
	ds_read_b128 v[186:189], v149 offset:18432
	ds_read_b128 v[206:209], v149 offset:19456
	ds_read_b128 v[210:213], v149 offset:20480
	ds_read_b128 v[214:217], v149 offset:21504
	ds_read_b128 v[224:227], v149 offset:22528
	ds_read_b128 v[228:231], v149 offset:23552
	global_load_lds_dwordx4 v[190:191], off
	s_add_i32 m0, s57, 0x2000
	s_add_u32 s58, s22, 0x10000
	v_lshl_add_u64 v[232:233], s[22:23], 0, v[128:129]
	s_addc_u32 s59, s23, 0
	s_add_i32 s57, s60, s42
	global_load_lds_dwordx4 v[232:233], off
	v_lshl_add_u64 v[234:235], s[58:59], 0, v[192:193]
	s_mov_b32 m0, s57
	v_lshl_add_u64 v[236:237], s[24:25], 0, v[130:131]
	global_load_lds_dwordx4 v[234:235], off
	v_lshl_add_u64 v[234:235], s[58:59], 0, v[128:129]
	s_add_i32 m0, s57, 0x2000
	s_nop 0
	global_load_lds_dwordx4 v[234:235], off
	v_lshl_add_u64 v[234:235], s[24:25], 0, v[132:133]
	s_mov_b32 m0, s43
	s_nop 0
	global_load_lds_dwordx4 v[234:235], off
	s_mov_b32 m0, s44
	s_nop 0
	global_load_lds_dwordx4 v[236:237], off
	s_waitcnt vmcnt(8)
	s_waitcnt lgkmcnt(0)
	s_barrier
; #define PG8_STAGE(bufoff, gbase, voff) do { _Pragma("unroll") for (int _i = 0; _i < 2; ++_i) \
;         __builtin_amdgcn_global_load_lds((const unsigned*)((const char*)(gbase) + (voff)[_i]), (PG8_LAS unsigned*)(lds + (bufoff) + ldsw + _i * 8192), 16, 0, 0); } while (0)
; #define PG8_LDA(dst, b, h) do { _Pragma("unroll") for (int m = 0; m < 4; ++m) _Pragma("unroll") for (int k = 0; k < 2; ++k) dst[m][k] = *(const PG8_LAS bf16x8*)(lds + PG8_SA(b, h) + aoff + m * 2048 + k * 1024); } while (0)
; #define PG8_LDB(dst, b, h) do { _Pragma("unroll") for (int n = 0; n < 2; ++n) _Pragma("unroll") for (int k = 0; k < 2; ++k) dst[n][k] = *(const PG8_LAS bf16x8*)(lds + PG8_SB(b, h) + boff + n * 2048 + k * 1024); } while (0)
; #define PG8_MMA(ai, bj, At, Bt) do { __builtin_amdgcn_s_setprio(1); _Pragma("unroll") for (int m = 0; m < 4; ++m) _Pragma("unroll") for (int n = 0; n < 2; ++n) _Pragma("unroll") for (int k = 0; k < 2; ++k) \
;         acc[ai][bj][m][n] = __builtin_amdgcn_mfma_f32_16x16x32_bf16(Bt[n][k], At[m][k], acc[ai][bj][m][n], 0, 0, 0); __builtin_amdgcn_s_setprio(0); } while (0)
; #define PG8_WAIT_V(n) asm volatile("s_waitcnt vmcnt(" #n ")" ::: "memory")
; #define PG8_WAIT_L(n) asm volatile("s_waitcnt lgkmcnt(" #n ")" ::: "memory")
; #define PG8_BAR __builtin_amdgcn_s_barrier()
; #define PG8_SCHED __builtin_amdgcn_sched_barrier(0)
; template <class Epi, class Sched, bool ALIGN_EPI = false, bool SP2 = false>
; __device__ __forceinline__ void gemm_phase(PG8_LAS unsigned char* lds, const Gemm g, const Sched& S, const Epi& E) {
;     ...
;             PG8_WAIT_V(8); PG8_WAIT_L(0); PG8_BAR; PG8_MMA(1, 0, At, B0); PG8_MMA(1, 1, At, B1); PG8_BAR; PG8_SCHED;
;             PG8_LDB(B0, 1, 0); PG8_LDB(B1, 1, 1); PG8_SCHED; PG8_LDA(At, 1, 0); PG8_STAGE(PG8_SA(0, 1), a2 + hstep, voffA);
;             PG8_WAIT_V(8); PG8_WAIT_L(0); PG8_BAR; PG8_MMA(0, 0, At, B0); PG8_MMA(0, 1, At, B1); PG8_BAR; PG8_SCHED;
	s_setprio 1
	s_waitcnt lgkmcnt(0)
	v_mfma_f32_16x16x32_bf16 v[60:63], v[138:141], v[178:181], v[60:63]
	v_mfma_f32_16x16x32_bf16 v[56:59], v[154:157], v[178:181], v[56:59]
	v_mfma_f32_16x16x32_bf16 v[48:51], v[138:141], v[186:189], v[48:51]
	v_mfma_f32_16x16x32_bf16 v[40:43], v[154:157], v[186:189], v[40:43]
	v_mfma_f32_16x16x32_bf16 v[32:35], v[138:141], v[210:213], v[32:35]
	v_mfma_f32_16x16x32_bf16 v[24:27], v[154:157], v[210:213], v[24:27]
	v_mfma_f32_16x16x32_bf16 v[16:19], v[138:141], v[224:227], v[16:19]
	v_mfma_f32_16x16x32_bf16 v[8:11], v[154:157], v[224:227], v[8:11]
	s_setprio 0
	s_setprio 1
	v_mfma_f32_16x16x32_bf16 v[60:63], v[150:153], v[182:185], v[60:63]
	v_mfma_f32_16x16x32_bf16 v[56:59], v[158:161], v[182:185], v[56:59]
	v_mfma_f32_16x16x32_bf16 v[48:51], v[150:153], v[206:209], v[48:51]
	v_mfma_f32_16x16x32_bf16 v[40:43], v[158:161], v[206:209], v[40:43]
	v_mfma_f32_16x16x32_bf16 v[32:35], v[150:153], v[214:217], v[32:35]
	v_mfma_f32_16x16x32_bf16 v[24:27], v[158:161], v[214:217], v[24:27]
	v_mfma_f32_16x16x32_bf16 v[16:19], v[150:153], v[228:231], v[16:19]
	v_mfma_f32_16x16x32_bf16 v[8:11], v[158:161], v[228:231], v[8:11]
	s_setprio 0
	s_setprio 1
	v_mfma_f32_16x16x32_bf16 v[52:55], v[162:165], v[178:181], v[52:55]
	v_mfma_f32_16x16x32_bf16 v[44:47], v[170:173], v[178:181], v[44:47]
	v_mfma_f32_16x16x32_bf16 v[36:39], v[162:165], v[186:189], v[36:39]
	v_mfma_f32_16x16x32_bf16 v[28:31], v[170:173], v[186:189], v[28:31]
	v_mfma_f32_16x16x32_bf16 v[20:23], v[162:165], v[210:213], v[20:23]
	v_mfma_f32_16x16x32_bf16 v[12:15], v[170:173], v[210:213], v[12:15]
	v_mfma_f32_16x16x32_bf16 v[4:7], v[162:165], v[224:227], v[4:7]
	v_mfma_f32_16x16x32_bf16 v[0:3], v[170:173], v[224:227], v[0:3]
	s_setprio 0
	s_setprio 1
	v_mfma_f32_16x16x32_bf16 v[52:55], v[166:169], v[182:185], v[52:55]
	v_mfma_f32_16x16x32_bf16 v[44:47], v[174:177], v[182:185], v[44:47]
	v_mfma_f32_16x16x32_bf16 v[36:39], v[166:169], v[206:209], v[36:39]
	v_mfma_f32_16x16x32_bf16 v[28:31], v[174:177], v[206:209], v[28:31]
	v_mfma_f32_16x16x32_bf16 v[20:23], v[166:169], v[214:217], v[20:23]
	v_mfma_f32_16x16x32_bf16 v[12:15], v[174:177], v[214:217], v[12:15]
	v_mfma_f32_16x16x32_bf16 v[4:7], v[166:169], v[228:231], v[4:7]
	v_mfma_f32_16x16x32_bf16 v[0:3], v[174:177], v[228:231], v[0:3]
	s_setprio 0
	s_barrier
	s_add_i32 s57, 0, 0x18000
	s_add_i32 s58, 0, 0x1c000
	v_add_u32_e32 v158, s57, v143
	v_add_u32_e32 v174, s58, v143
	ds_read_b128 v[138:141], v158
	ds_read_b128 v[150:153], v158 offset:1024
	ds_read_b128 v[154:157], v158 offset:2048
	ds_read_b128 v[158:161], v158 offset:3072
	ds_read_b128 v[162:165], v174
	ds_read_b128 v[166:169], v174 offset:1024
	ds_read_b128 v[170:173], v174 offset:2048
	ds_read_b128 v[174:177], v174 offset:3072
	s_add_u32 s24, s24, 0x40000
	s_addc_u32 s25, s25, 0
	s_mov_b32 m0, s45
	v_lshl_add_u64 v[238:239], s[24:25], 0, v[132:133]
	ds_read_b128 v[178:181], v149 offset:32768
	ds_read_b128 v[182:185], v149 offset:33792
	ds_read_b128 v[186:189], v149 offset:34816
	ds_read_b128 v[206:209], v149 offset:35840
	ds_read_b128 v[210:213], v149 offset:36864
	ds_read_b128 v[214:217], v149 offset:37888
	ds_read_b128 v[224:227], v149 offset:38912
	ds_read_b128 v[228:231], v149 offset:39936
	global_load_lds_dwordx4 v[238:239], off
	v_lshl_add_u64 v[238:239], s[24:25], 0, v[130:131]
	s_mov_b32 m0, s46
	s_nop 0
	global_load_lds_dwordx4 v[238:239], off
	s_waitcnt vmcnt(8)
	s_waitcnt lgkmcnt(0)
	s_barrier
	s_setprio 1
	s_waitcnt lgkmcnt(0)
	v_mfma_f32_16x16x32_bf16 v[124:127], v[138:141], v[178:181], v[124:127]
	v_mfma_f32_16x16x32_bf16 v[120:123], v[154:157], v[178:181], v[120:123]
	v_mfma_f32_16x16x32_bf16 v[112:115], v[138:141], v[186:189], v[112:115]
	v_mfma_f32_16x16x32_bf16 v[104:107], v[154:157], v[186:189], v[104:107]
	v_mfma_f32_16x16x32_bf16 v[96:99], v[138:141], v[210:213], v[96:99]
	v_mfma_f32_16x16x32_bf16 v[88:91], v[154:157], v[210:213], v[88:91]
	v_mfma_f32_16x16x32_bf16 v[80:83], v[138:141], v[224:227], v[80:83]
	v_mfma_f32_16x16x32_bf16 v[72:75], v[154:157], v[224:227], v[72:75]
	s_setprio 0
	s_setprio 1
	v_mfma_f32_16x16x32_bf16 v[124:127], v[150:153], v[182:185], v[124:127]
	v_mfma_f32_16x16x32_bf16 v[120:123], v[158:161], v[182:185], v[120:123]
	v_mfma_f32_16x16x32_bf16 v[112:115], v[150:153], v[206:209], v[112:115]
	v_mfma_f32_16x16x32_bf16 v[104:107], v[158:161], v[206:209], v[104:107]
	v_mfma_f32_16x16x32_bf16 v[96:99], v[150:153], v[214:217], v[96:99]
	v_mfma_f32_16x16x32_bf16 v[88:91], v[158:161], v[214:217], v[88:91]
	v_mfma_f32_16x16x32_bf16 v[80:83], v[150:153], v[228:231], v[80:83]
	v_mfma_f32_16x16x32_bf16 v[72:75], v[158:161], v[228:231], v[72:75]
	s_setprio 0
	s_setprio 1
	v_mfma_f32_16x16x32_bf16 v[116:119], v[162:165], v[178:181], v[116:119]
	v_mfma_f32_16x16x32_bf16 v[108:111], v[170:173], v[178:181], v[108:111]
	v_mfma_f32_16x16x32_bf16 v[100:103], v[162:165], v[186:189], v[100:103]
	v_mfma_f32_16x16x32_bf16 v[92:95], v[170:173], v[186:189], v[92:95]
	v_mfma_f32_16x16x32_bf16 v[84:87], v[162:165], v[210:213], v[84:87]
	v_mfma_f32_16x16x32_bf16 v[76:79], v[170:173], v[210:213], v[76:79]
	v_mfma_f32_16x16x32_bf16 v[68:71], v[162:165], v[224:227], v[68:71]
	v_mfma_f32_16x16x32_bf16 v[64:67], v[170:173], v[224:227], v[64:67]
	s_setprio 0
	s_setprio 1
	v_mfma_f32_16x16x32_bf16 v[116:119], v[166:169], v[182:185], v[116:119]
	v_mfma_f32_16x16x32_bf16 v[108:111], v[174:177], v[182:185], v[108:111]
	v_mfma_f32_16x16x32_bf16 v[100:103], v[166:169], v[206:209], v[100:103]
	v_mfma_f32_16x16x32_bf16 v[92:95], v[174:177], v[206:209], v[92:95]
	v_mfma_f32_16x16x32_bf16 v[84:87], v[166:169], v[214:217], v[84:87]
	v_mfma_f32_16x16x32_bf16 v[76:79], v[174:177], v[214:217], v[76:79]
	v_mfma_f32_16x16x32_bf16 v[68:71], v[166:169], v[228:231], v[68:71]
	v_mfma_f32_16x16x32_bf16 v[64:67], v[174:177], v[228:231], v[64:67]
	s_setprio 0
	s_barrier
; #define PG8_STAGE(bufoff, gbase, voff) do { _Pragma("unroll") for (int _i = 0; _i < 2; ++_i) \
;         __builtin_amdgcn_global_load_lds((const unsigned*)((const char*)(gbase) + (voff)[_i]), (PG8_LAS unsigned*)(lds + (bufoff) + ldsw + _i * 8192), 16, 0, 0); } while (0)
; #define PG8_LDA(dst, b, h) do { _Pragma("unroll") for (int m = 0; m < 4; ++m) _Pragma("unroll") for (int k = 0; k < 2; ++k) dst[m][k] = *(const PG8_LAS bf16x8*)(lds + PG8_SA(b, h) + aoff + m * 2048 + k * 1024); } while (0)
; #define PG8_MMA(ai, bj, At, Bt) do { __builtin_amdgcn_s_setprio(1); _Pragma("unroll") for (int m = 0; m < 4; ++m) _Pragma("unroll") for (int n = 0; n < 2; ++n) _Pragma("unroll") for (int k = 0; k < 2; ++k) \
;         acc[ai][bj][m][n] = __builtin_amdgcn_mfma_f32_16x16x32_bf16(Bt[n][k], At[m][k], acc[ai][bj][m][n], 0, 0, 0); __builtin_amdgcn_s_setprio(0); } while (0)
; #define PG8_WAIT_V(n) asm volatile("s_waitcnt vmcnt(" #n ")" ::: "memory")
; #define PG8_WAIT_L(n) asm volatile("s_waitcnt lgkmcnt(" #n ")" ::: "memory")
; #define PG8_BAR __builtin_amdgcn_s_barrier()
; #define PG8_SCHED __builtin_amdgcn_sched_barrier(0)
; template <class Epi, class Sched, bool ALIGN_EPI = false, bool SP2 = false>
; __device__ __forceinline__ void gemm_phase(PG8_LAS unsigned char* lds, const Gemm g, const Sched& S, const Epi& E) {
;     ...
;         for (int t = 0; t < nt; t += 2) {
;             const bool last = (t == nt - 2);
;     ...
;             PG8_LDA(At, 1, 1); PG8_STAGE(PG8_SB(1, 0), b3, voffB); PG8_STAGE(PG8_SB(1, 1), b3 + hstepB, voffB); PG8_STAGE(PG8_SA(1, 0), a3, voffA);
;             PG8_WAIT_V(8); PG8_WAIT_L(0); PG8_BAR; PG8_MMA(1, 0, At, B0); PG8_MMA(1, 1, At, B1); PG8_BAR; PG8_SCHED;
	s_add_i32 s24, s57, s42
	v_lshl_add_u64 v[190:191], v[190:191], 0, s[36:37]
	s_mov_b32 m0, s24
	ds_read_b128 v[178:181], v149 offset:49152
	ds_read_b128 v[182:185], v149 offset:50176
	ds_read_b128 v[186:189], v149 offset:51200
	ds_read_b128 v[206:209], v149 offset:52224
	ds_read_b128 v[210:213], v149 offset:53248
	ds_read_b128 v[214:217], v149 offset:54272
	ds_read_b128 v[224:227], v149 offset:55296
	ds_read_b128 v[228:231], v149 offset:56320
	global_load_lds_dwordx4 v[190:191], off
	s_add_i32 m0, s24, 0x2000
	s_add_u32 s22, s22, 0x10080
	v_lshl_add_u64 v[190:191], v[232:233], 0, s[36:37]
	s_addc_u32 s23, s23, 0
	s_add_i32 s24, s58, s42
	global_load_lds_dwordx4 v[190:191], off
	v_lshl_add_u64 v[190:191], s[22:23], 0, v[192:193]
	s_mov_b32 m0, s24
	s_nop 0
	global_load_lds_dwordx4 v[190:191], off
	v_lshl_add_u64 v[190:191], s[22:23], 0, v[128:129]
	s_add_i32 m0, s24, 0x2000
	s_nop 0
	global_load_lds_dwordx4 v[190:191], off
	v_lshl_add_u64 v[190:191], v[234:235], 0, s[36:37]
	s_mov_b32 m0, s47
	s_nop 0
	global_load_lds_dwordx4 v[190:191], off
	v_lshl_add_u64 v[190:191], v[236:237], 0, s[36:37]
	s_mov_b32 m0, s48
	s_nop 0
	global_load_lds_dwordx4 v[190:191], off
	s_waitcnt vmcnt(8)
	s_waitcnt lgkmcnt(0)
	s_barrier
	s_setprio 1
	s_waitcnt lgkmcnt(0)
	v_mfma_f32_16x16x32_bf16 v[60:63], v[138:141], v[178:181], v[60:63]
	v_mfma_f32_16x16x32_bf16 v[56:59], v[154:157], v[178:181], v[56:59]
	v_mfma_f32_16x16x32_bf16 v[48:51], v[138:141], v[186:189], v[48:51]
	v_mfma_f32_16x16x32_bf16 v[40:43], v[154:157], v[186:189], v[40:43]
	v_mfma_f32_16x16x32_bf16 v[32:35], v[138:141], v[210:213], v[32:35]
	v_mfma_f32_16x16x32_bf16 v[24:27], v[154:157], v[210:213], v[24:27]
	v_mfma_f32_16x16x32_bf16 v[16:19], v[138:141], v[224:227], v[16:19]
	v_mfma_f32_16x16x32_bf16 v[8:11], v[154:157], v[224:227], v[8:11]
	s_setprio 0
	s_setprio 1
	v_mfma_f32_16x16x32_bf16 v[60:63], v[150:153], v[182:185], v[60:63]
	v_mfma_f32_16x16x32_bf16 v[56:59], v[158:161], v[182:185], v[56:59]
	v_mfma_f32_16x16x32_bf16 v[48:51], v[150:153], v[206:209], v[48:51]
	v_mfma_f32_16x16x32_bf16 v[40:43], v[158:161], v[206:209], v[40:43]
	v_mfma_f32_16x16x32_bf16 v[32:35], v[150:153], v[214:217], v[32:35]
	v_mfma_f32_16x16x32_bf16 v[24:27], v[158:161], v[214:217], v[24:27]
	v_mfma_f32_16x16x32_bf16 v[16:19], v[150:153], v[228:231], v[16:19]
	v_mfma_f32_16x16x32_bf16 v[8:11], v[158:161], v[228:231], v[8:11]
	s_setprio 0
	s_setprio 1
	v_mfma_f32_16x16x32_bf16 v[52:55], v[162:165], v[178:181], v[52:55]
	v_mfma_f32_16x16x32_bf16 v[44:47], v[170:173], v[178:181], v[44:47]
	v_mfma_f32_16x16x32_bf16 v[36:39], v[162:165], v[186:189], v[36:39]
	v_mfma_f32_16x16x32_bf16 v[28:31], v[170:173], v[186:189], v[28:31]
	v_mfma_f32_16x16x32_bf16 v[20:23], v[162:165], v[210:213], v[20:23]
	v_mfma_f32_16x16x32_bf16 v[12:15], v[170:173], v[210:213], v[12:15]
	v_mfma_f32_16x16x32_bf16 v[4:7], v[162:165], v[224:227], v[4:7]
	v_mfma_f32_16x16x32_bf16 v[0:3], v[170:173], v[224:227], v[0:3]
	s_setprio 0
	s_setprio 1
	v_mfma_f32_16x16x32_bf16 v[52:55], v[166:169], v[182:185], v[52:55]
	v_mfma_f32_16x16x32_bf16 v[44:47], v[174:177], v[182:185], v[44:47]
	v_mfma_f32_16x16x32_bf16 v[36:39], v[166:169], v[206:209], v[36:39]
	v_mfma_f32_16x16x32_bf16 v[28:31], v[174:177], v[206:209], v[28:31]
	v_mfma_f32_16x16x32_bf16 v[20:23], v[166:169], v[214:217], v[20:23]
	v_mfma_f32_16x16x32_bf16 v[12:15], v[174:177], v[214:217], v[12:15]
	v_mfma_f32_16x16x32_bf16 v[4:7], v[166:169], v[228:231], v[4:7]
	v_mfma_f32_16x16x32_bf16 v[0:3], v[174:177], v[228:231], v[0:3]
	s_setprio 0
	s_barrier
	s_add_i32 s56, s56, 2
	s_add_u32 s54, s54, 0x100
	s_addc_u32 s55, s55, 0
	s_add_u32 s20, s20, 0x100
	s_addc_u32 s21, s21, 0
	s_cmp_gt_u32 s56, 13
	s_cbranch_scc0 .LBB0_304
	s_and_b64 vcc, exec, s[10:11]
	s_cbranch_vccz .LBB0_307
	s_barrier
